# pooling items: all W^T fragment loads issued up front (hipcc: four drained batches of flat loads)
# baseline (speedup 1.0000x reference)
.LBB0_753:
	s_waitcnt vmcnt(0)
	v_lshlrev_b32_e32 v1, 16, v1
	v_lshlrev_b32_e32 v6, 16, v6
	v_cndmask_b32_e64 v1, v1, v5, s[22:23]
	v_lshlrev_b32_e32 v7, 16, v7
	v_cndmask_b32_e64 v4, v6, v4, s[22:23]
	v_add_f32_e32 v5, 0, v1
	v_lshlrev_b32_e32 v10, 16, v10
	v_cndmask_b32_e64 v7, v7, v8, s[22:23]
	v_add_f32_e32 v5, v5, v4
	v_lshlrev_b32_e32 v11, 16, v11
	v_cndmask_b32_e64 v9, v10, v9, s[22:23]
	v_add_f32_e32 v5, v5, v7
	v_lshlrev_b32_e32 v14, 16, v14
	v_cndmask_b32_e64 v11, v11, v12, s[22:23]
	v_add_f32_e32 v5, v5, v9
	v_lshlrev_b32_e32 v15, 16, v15
	v_cndmask_b32_e64 v13, v14, v13, s[22:23]
	v_add_f32_e32 v5, v5, v11
	v_lshlrev_b32_e32 v18, 16, v18
	v_cndmask_b32_e64 v15, v15, v16, s[22:23]
	v_add_f32_e32 v5, v5, v13
	v_lshlrev_b32_e32 v19, 16, v19
	v_cndmask_b32_e64 v17, v18, v17, s[22:23]
	v_add_f32_e32 v5, v5, v15
	v_lshlrev_b32_e32 v26, 16, v26
	v_cndmask_b32_e64 v19, v19, v22, s[22:23]
	v_add_f32_e32 v5, v5, v17
	v_lshlrev_b32_e32 v29, 16, v29
	v_cndmask_b32_e64 v23, v26, v23, s[22:23]
	v_add_f32_e32 v5, v5, v19
	v_lshlrev_b32_e32 v34, 16, v34
	v_cndmask_b32_e64 v29, v29, v31, s[22:23]
	v_add_f32_e32 v5, v5, v23
	v_lshlrev_b32_e32 v61, 16, v61
	v_lshlrev_b32_e32 v143, 16, v41
	v_lshlrev_b32_e32 v41, 16, v21
	v_cndmask_b32_e64 v32, v34, v32, s[22:23]
	v_add_f32_e32 v5, v5, v29
	v_lshlrev_b32_e32 v64, 16, v64
	v_lshlrev_b32_e32 v141, 16, v44
	v_lshlrev_b32_e32 v147, 16, v37
	v_lshlrev_b32_e32 v37, 16, v25
	v_cndmask_b32_e64 v44, v61, v59, s[22:23]
	v_cndmask_b32_e64 v59, v41, v24, s[22:23]
	v_add_f32_e32 v5, v5, v32
	v_lshlrev_b32_e32 v57, 16, v57
	v_lshlrev_b32_e32 v142, 16, v42
	v_lshlrev_b32_e32 v149, 16, v35
	v_lshlrev_b32_e32 v35, 16, v28
	v_cndmask_b32_e64 v42, v64, v58, s[22:23]
	v_cndmask_b32_e64 v58, v37, v20, s[22:23]
	s_add_i32 s0, s12, s36
	v_add_f32_e32 v5, v5, v59
	v_lshlrev_b32_e32 v137, 16, v48
	v_cndmask_b32_e64 v48, v57, v55, s[22:23]
	v_cndmask_b32_e64 v57, v35, v30, s[22:23]
	v_add_f32_e32 v5, v5, v58
	s_min_u32 s1, s0, 15
	v_lshlrev_b32_e32 v153, 16, v33
	v_add_f32_e32 v5, v5, v57
	s_add_i32 s1, s1, 1
	v_add_f32_e32 v5, v5, v153
	v_cvt_f32_ubyte0_e32 v6, s1
	global_load_ushort v3, v151, s[10:11]
	global_load_ushort v78, v151, s[66:67]
	global_load_ushort v79, v151, s[60:61]
	global_load_ushort v80, v151, s[58:59]
	global_load_ushort v81, v151, s[56:57]
	global_load_ushort v82, v151, s[74:75]
	global_load_ushort v83, v151, s[72:73]
	global_load_ushort v84, v151, s[70:71]
	global_load_ushort v85, v151, s[68:69]
	global_load_ushort v86, v151, s[34:35]
	global_load_ushort v87, v151, s[2:3]
	global_load_ushort v88, v151, s[42:43]
	global_load_ushort v89, v151, s[46:47]
	global_load_ushort v90, v151, s[50:51]
	global_load_ushort v133, v151, s[40:41]
	global_load_ushort v135, v151, s[38:39]
	v_div_scale_f32 v8, s[2:3], v6, v6, v5
	v_rcp_f32_e32 v10, v8
	s_or_b32 s1, s0, 1
	s_min_u32 s1, s1, 15
	v_lshlrev_b32_e32 v16, 16, v49
	v_fma_f32 v18, -v8, v10, 1.0
	v_fmac_f32_e32 v10, v18, v10
	v_div_scale_f32 v18, vcc, v5, v6, v5
	v_mul_f32_e32 v22, v18, v10
	v_fma_f32 v26, -v8, v22, v18
	v_fmac_f32_e32 v22, v26, v10
	v_fma_f32 v8, -v8, v22, v18
	v_div_fmas_f32 v8, v8, v10, v22
	v_sub_f32_e32 v1, v5, v1
	s_add_i32 s1, s1, 1
	v_div_fixup_f32 v8, v8, v6, v5
	v_add_f32_e32 v1, v1, v16
	v_cvt_f32_ubyte0_e32 v5, s1
	v_div_scale_f32 v10, s[2:3], v5, v5, v1
	v_rcp_f32_e32 v18, v10
	v_sub_f32_e32 v8, v8, v153
	v_bfe_u32 v22, v8, 16, 1
	v_add3_u32 v8, v8, v22, s33
	ds_write_b16_d16_hi v101, v8
	v_fma_f32 v8, -v10, v18, 1.0
	v_fmac_f32_e32 v18, v8, v18
	v_div_scale_f32 v8, vcc, v1, v5, v1
	v_mul_f32_e32 v22, v8, v18
	v_fma_f32 v26, -v10, v22, v8
	v_fmac_f32_e32 v22, v26, v18
	v_fma_f32 v8, -v10, v22, v8
	s_or_b32 s1, s0, 2
	v_div_fmas_f32 v8, v8, v18, v22
	s_min_u32 s1, s1, 15
	v_lshlrev_b32_e32 v14, 16, v50
	v_div_fixup_f32 v8, v8, v5, v1
	v_sub_f32_e32 v1, v1, v4
	s_add_i32 s1, s1, 1
	v_add_f32_e32 v1, v1, v14
	v_cvt_f32_ubyte0_e32 v4, s1
	v_div_scale_f32 v10, s[2:3], v4, v4, v1
	v_sub_f32_e32 v8, v8, v16
	v_rcp_f32_e32 v16, v10
	v_bfe_u32 v18, v8, 16, 1
	v_add3_u32 v8, v8, v18, s33
	ds_write_b16_d16_hi v101, v8 offset:272
	v_fma_f32 v8, -v10, v16, 1.0
	v_fmac_f32_e32 v16, v8, v16
	v_div_scale_f32 v8, vcc, v1, v4, v1
	v_mul_f32_e32 v18, v8, v16
	v_fma_f32 v22, -v10, v18, v8
	v_fmac_f32_e32 v18, v22, v16
	v_fma_f32 v8, -v10, v18, v8
	s_or_b32 s1, s0, 3
	v_div_fmas_f32 v8, v8, v16, v18
	s_min_u32 s1, s1, 15
	v_lshlrev_b32_e32 v12, 16, v51
	v_div_fixup_f32 v8, v8, v4, v1
	v_sub_f32_e32 v1, v1, v7
	s_add_i32 s1, s1, 1
	v_add_f32_e32 v1, v1, v12
	v_cvt_f32_ubyte0_e32 v7, s1
	v_div_scale_f32 v10, s[2:3], v7, v7, v1
	v_sub_f32_e32 v8, v8, v14
	v_rcp_f32_e32 v14, v10
	v_bfe_u32 v16, v8, 16, 1
	v_add3_u32 v8, v8, v16, s33
	ds_write_b16_d16_hi v101, v8 offset:544
	v_fma_f32 v8, -v10, v14, 1.0
	v_fmac_f32_e32 v14, v8, v14
	v_div_scale_f32 v8, vcc, v1, v7, v1
	v_mul_f32_e32 v16, v8, v14
	v_fma_f32 v18, -v10, v16, v8
	v_fmac_f32_e32 v16, v18, v14
	v_fma_f32 v8, -v10, v16, v8
	s_or_b32 s1, s0, 4
	v_div_fmas_f32 v8, v8, v14, v16
	s_min_u32 s1, s1, 15
	v_div_fixup_f32 v8, v8, v7, v1
	v_sub_f32_e32 v1, v1, v9
	s_add_i32 s1, s1, 1
	v_add_f32_e32 v1, v1, v149
	v_cvt_f32_ubyte0_e32 v9, s1
	v_div_scale_f32 v10, s[2:3], v9, v9, v1
	v_sub_f32_e32 v8, v8, v12
	v_rcp_f32_e32 v12, v10
	v_bfe_u32 v14, v8, 16, 1
	v_add3_u32 v8, v8, v14, s33
	ds_write_b16_d16_hi v101, v8 offset:816
	v_fma_f32 v8, -v10, v12, 1.0
	v_fmac_f32_e32 v12, v8, v12
	v_div_scale_f32 v8, vcc, v1, v9, v1
	v_mul_f32_e32 v14, v8, v12
	v_fma_f32 v16, -v10, v14, v8
	v_fmac_f32_e32 v14, v16, v12
	v_fma_f32 v8, -v10, v14, v8
	s_or_b32 s1, s0, 5
	v_div_fmas_f32 v8, v8, v12, v14
	s_min_u32 s1, s1, 15
	v_lshlrev_b32_e32 v148, 16, v36
	v_div_fixup_f32 v8, v8, v9, v1
	v_sub_f32_e32 v1, v1, v11
	s_add_i32 s1, s1, 1
	v_add_f32_e32 v1, v1, v148
	v_cvt_f32_ubyte0_e32 v10, s1
	v_div_scale_f32 v11, s[2:3], v10, v10, v1
	v_rcp_f32_e32 v12, v11
	v_sub_f32_e32 v8, v8, v149
	v_bfe_u32 v14, v8, 16, 1
	v_add3_u32 v8, v8, v14, s33
	ds_write_b16_d16_hi v101, v8 offset:1088
	v_fma_f32 v8, -v11, v12, 1.0
	v_fmac_f32_e32 v12, v8, v12
	v_div_scale_f32 v8, vcc, v1, v10, v1
	v_mul_f32_e32 v14, v8, v12
	v_fma_f32 v16, -v11, v14, v8
	v_fmac_f32_e32 v14, v16, v12
	v_fma_f32 v8, -v11, v14, v8
	s_or_b32 s1, s0, 6
	v_div_fmas_f32 v8, v8, v12, v14
	s_min_u32 s1, s1, 15
	v_div_fixup_f32 v8, v8, v10, v1
	v_sub_f32_e32 v1, v1, v13
	s_add_i32 s1, s1, 1
	v_add_f32_e32 v1, v1, v147
	v_cvt_f32_ubyte0_e32 v11, s1
	v_div_scale_f32 v12, s[2:3], v11, v11, v1
	v_rcp_f32_e32 v13, v12
	v_sub_f32_e32 v8, v8, v148
	v_bfe_u32 v14, v8, 16, 1
	v_add3_u32 v8, v8, v14, s33
	ds_write_b16_d16_hi v101, v8 offset:1360
	v_fma_f32 v8, -v12, v13, 1.0
	v_fmac_f32_e32 v13, v8, v13
	v_div_scale_f32 v8, vcc, v1, v11, v1
	v_mul_f32_e32 v14, v8, v13
	v_fma_f32 v16, -v12, v14, v8
	v_fmac_f32_e32 v14, v16, v13
	v_fma_f32 v8, -v12, v14, v8
	s_or_b32 s1, s0, 7
	v_div_fmas_f32 v8, v8, v13, v14
	s_min_u32 s1, s1, 15
	v_lshlrev_b32_e32 v146, 16, v38
	v_div_fixup_f32 v8, v8, v11, v1
	v_sub_f32_e32 v1, v1, v15
	s_add_i32 s1, s1, 1
	v_add_f32_e32 v1, v1, v146
	v_cvt_f32_ubyte0_e32 v12, s1
	v_div_scale_f32 v13, s[2:3], v12, v12, v1
	v_rcp_f32_e32 v14, v13
	v_sub_f32_e32 v8, v8, v147
	v_bfe_u32 v15, v8, 16, 1
	v_add3_u32 v8, v8, v15, s33
	ds_write_b16_d16_hi v101, v8 offset:1632
	v_fma_f32 v8, -v13, v14, 1.0
	v_fmac_f32_e32 v14, v8, v14
	v_div_scale_f32 v8, vcc, v1, v12, v1
	v_mul_f32_e32 v15, v8, v14
	v_fma_f32 v16, -v13, v15, v8
	v_fmac_f32_e32 v15, v16, v14
	v_fma_f32 v8, -v13, v15, v8
	s_or_b32 s1, s0, 8
	v_div_fmas_f32 v8, v8, v14, v15
	s_min_u32 s1, s1, 15
	v_lshlrev_b32_e32 v144, 16, v40
	v_div_fixup_f32 v8, v8, v12, v1
	v_sub_f32_e32 v1, v1, v17
	s_add_i32 s1, s1, 1
	v_add_f32_e32 v1, v1, v144
	v_cvt_f32_ubyte0_e32 v13, s1
	v_div_scale_f32 v14, s[2:3], v13, v13, v1
	v_rcp_f32_e32 v15, v14
	v_sub_f32_e32 v8, v8, v146
	v_bfe_u32 v16, v8, 16, 1
	v_add3_u32 v8, v8, v16, s33
	ds_write_b16_d16_hi v101, v8 offset:1904
	v_fma_f32 v8, -v14, v15, 1.0
	v_fmac_f32_e32 v15, v8, v15
	v_div_scale_f32 v8, vcc, v1, v13, v1
	v_mul_f32_e32 v16, v8, v15
	v_fma_f32 v17, -v14, v16, v8
	v_fmac_f32_e32 v16, v17, v15
	v_fma_f32 v8, -v14, v16, v8
	s_or_b32 s1, s0, 9
	v_div_fmas_f32 v8, v8, v15, v16
	s_min_u32 s1, s1, 15
	v_div_fixup_f32 v8, v8, v13, v1
	v_sub_f32_e32 v1, v1, v19
	s_add_i32 s1, s1, 1
	v_add_f32_e32 v1, v1, v143
	v_cvt_f32_ubyte0_e32 v14, s1
	v_div_scale_f32 v15, s[2:3], v14, v14, v1
	v_rcp_f32_e32 v16, v15
	v_sub_f32_e32 v8, v8, v144
	v_bfe_u32 v17, v8, 16, 1
	v_add3_u32 v8, v8, v17, s33
	ds_write_b16_d16_hi v101, v8 offset:2176
	v_fma_f32 v8, -v15, v16, 1.0
	v_fmac_f32_e32 v16, v8, v16
	v_div_scale_f32 v8, vcc, v1, v14, v1
	v_mul_f32_e32 v17, v8, v16
	v_fma_f32 v18, -v15, v17, v8
	v_fmac_f32_e32 v17, v18, v16
	v_fma_f32 v8, -v15, v17, v8
	s_or_b32 s1, s0, 10
	v_div_fmas_f32 v8, v8, v16, v17
	s_min_u32 s1, s1, 15
	v_div_fixup_f32 v8, v8, v14, v1
	v_sub_f32_e32 v1, v1, v23
	s_add_i32 s1, s1, 1
	v_add_f32_e32 v1, v1, v142
	v_cvt_f32_ubyte0_e32 v15, s1
	v_div_scale_f32 v16, s[2:3], v15, v15, v1
	v_rcp_f32_e32 v17, v16
	v_sub_f32_e32 v8, v8, v143
	v_bfe_u32 v18, v8, 16, 1
	v_add3_u32 v8, v8, v18, s33
	ds_write_b16_d16_hi v101, v8 offset:2448
	v_fma_f32 v8, -v16, v17, 1.0
	v_fmac_f32_e32 v17, v8, v17
	v_div_scale_f32 v8, vcc, v1, v15, v1
	v_mul_f32_e32 v18, v8, v17
	v_fma_f32 v19, -v16, v18, v8
	v_fmac_f32_e32 v18, v19, v17
	v_fma_f32 v8, -v16, v18, v8
	s_or_b32 s1, s0, 11
	v_div_fmas_f32 v8, v8, v17, v18
	s_min_u32 s1, s1, 15
	v_div_fixup_f32 v8, v8, v15, v1
	v_sub_f32_e32 v1, v1, v29
	s_add_i32 s1, s1, 1
	v_add_f32_e32 v1, v1, v141
	v_cvt_f32_ubyte0_e32 v16, s1
	v_div_scale_f32 v17, s[2:3], v16, v16, v1
	v_rcp_f32_e32 v18, v17
	v_sub_f32_e32 v8, v8, v142
	v_bfe_u32 v19, v8, 16, 1
	v_add3_u32 v8, v8, v19, s33
	ds_write_b16_d16_hi v101, v8 offset:2720
	v_fma_f32 v8, -v17, v18, 1.0
	v_fmac_f32_e32 v18, v8, v18
	v_div_scale_f32 v8, vcc, v1, v16, v1
	v_mul_f32_e32 v19, v8, v18
	v_fma_f32 v22, -v17, v19, v8
	v_fmac_f32_e32 v19, v22, v18
	v_fma_f32 v8, -v17, v19, v8
	s_or_b32 s1, s0, 12
	v_div_fmas_f32 v8, v8, v18, v19
	s_min_u32 s1, s1, 15
	v_lshlrev_b32_e32 v140, 16, v45
	v_div_fixup_f32 v8, v8, v16, v1
	v_sub_f32_e32 v1, v1, v32
	s_add_i32 s1, s1, 1
	v_add_f32_e32 v1, v1, v140
	v_cvt_f32_ubyte0_e32 v17, s1
	v_div_scale_f32 v18, s[2:3], v17, v17, v1
	v_rcp_f32_e32 v19, v18
	v_sub_f32_e32 v8, v8, v141
	v_bfe_u32 v22, v8, 16, 1
	v_add3_u32 v8, v8, v22, s33
	ds_write_b16_d16_hi v101, v8 offset:2992
	v_fma_f32 v8, -v18, v19, 1.0
	v_fmac_f32_e32 v19, v8, v19
	v_div_scale_f32 v8, vcc, v1, v17, v1
	v_mul_f32_e32 v22, v8, v19
	v_fma_f32 v23, -v18, v22, v8
	v_fmac_f32_e32 v22, v23, v19
	v_fma_f32 v8, -v18, v22, v8
	s_or_b32 s1, s0, 13
	v_div_fmas_f32 v8, v8, v19, v22
	s_min_u32 s1, s1, 15
	v_lshlrev_b32_e32 v139, 16, v46
	v_div_fixup_f32 v8, v8, v17, v1
	v_sub_f32_e32 v1, v1, v59
	s_add_i32 s1, s1, 1
	v_add_f32_e32 v1, v1, v139
	v_cvt_f32_ubyte0_e32 v18, s1
	v_div_scale_f32 v19, s[2:3], v18, v18, v1
	v_rcp_f32_e32 v22, v19
	v_sub_f32_e32 v8, v8, v140
	v_bfe_u32 v23, v8, 16, 1
	v_add3_u32 v8, v8, v23, s33
	ds_write_b16_d16_hi v101, v8 offset:3264
	v_fma_f32 v8, -v19, v22, 1.0
	v_fmac_f32_e32 v22, v8, v22
	v_div_scale_f32 v8, vcc, v1, v18, v1
	v_mul_f32_e32 v23, v8, v22
	v_fma_f32 v26, -v19, v23, v8
	v_fmac_f32_e32 v23, v26, v22
	v_fma_f32 v8, -v19, v23, v8
	s_or_b32 s0, s0, 14
	v_div_fmas_f32 v8, v8, v22, v23
	s_min_u32 s0, s0, 15
	v_lshlrev_b32_e32 v138, 16, v47
	v_div_fixup_f32 v8, v8, v18, v1
	v_sub_f32_e32 v1, v1, v58
	s_add_i32 s0, s0, 1
	v_add_f32_e32 v1, v1, v138
	v_cvt_f32_ubyte0_e32 v19, s0
	v_div_scale_f32 v22, s[0:1], v19, v19, v1
	v_rcp_f32_e32 v23, v22
	v_sub_f32_e32 v8, v8, v139
	v_bfe_u32 v26, v8, 16, 1
	v_add3_u32 v8, v8, v26, s33
	ds_write_b16_d16_hi v101, v8 offset:3536
	v_fma_f32 v8, -v22, v23, 1.0
	v_fmac_f32_e32 v23, v8, v23
	v_div_scale_f32 v8, vcc, v1, v19, v1
	v_mul_f32_e32 v26, v8, v23
	v_fma_f32 v29, -v22, v26, v8
	v_fmac_f32_e32 v26, v29, v23
	v_fma_f32 v8, -v22, v26, v8
	v_div_fmas_f32 v8, v8, v23, v26
	v_div_fixup_f32 v8, v8, v19, v1
	v_sub_f32_e32 v8, v8, v138
	v_lshlrev_b32_e32 v56, 16, v56
	v_lshlrev_b32_e32 v52, 16, v52
	v_bfe_u32 v22, v8, 16, 1
	v_lshlrev_b32_e32 v136, 16, v53
	v_cndmask_b32_e64 v53, v56, v43, s[22:23]
	v_cndmask_b32_e64 v56, v52, v27, s[22:23]
	v_add3_u32 v8, v8, v22, s33
	v_cndmask_b32_e64 v55, v136, v39, s[22:23]
	ds_write_b16_d16_hi v101, v8 offset:3808
	v_add_f32_e32 v8, 0, v56
	v_add_f32_e32 v8, v8, v55
	v_lshlrev_b32_e32 v60, 16, v60
	v_add_f32_e32 v8, v8, v53
	v_cndmask_b32_e64 v46, v60, v54, s[22:23]
	v_add_f32_e32 v8, v8, v48
	v_add_f32_e32 v8, v8, v46
	v_lshlrev_b32_e32 v65, 16, v65
	v_add_f32_e32 v8, v8, v44
	v_lshlrev_b32_e32 v68, 16, v68
	v_cndmask_b32_e64 v40, v65, v63, s[22:23]
	v_add_f32_e32 v8, v8, v42
	v_lshlrev_b32_e32 v69, 16, v69
	v_cndmask_b32_e64 v38, v68, v62, s[22:23]
	v_add_f32_e32 v8, v8, v40
	v_lshlrev_b32_e32 v72, 16, v72
	v_cndmask_b32_e64 v36, v69, v67, s[22:23]
	v_add_f32_e32 v8, v8, v38
	v_lshlrev_b32_e32 v73, 16, v73
	v_cndmask_b32_e64 v33, v72, v66, s[22:23]
	v_add_f32_e32 v8, v8, v36
	v_lshlrev_b32_e32 v76, 16, v76
	v_cndmask_b32_e64 v28, v73, v71, s[22:23]
	v_add_f32_e32 v8, v8, v33
	v_lshlrev_b32_e32 v77, 16, v77
	v_cndmask_b32_e64 v25, v76, v70, s[22:23]
	v_add_f32_e32 v8, v8, v28
	v_lshlrev_b32_e32 v2, 16, v2
	v_cndmask_b32_e64 v21, v77, v75, s[22:23]
	v_add_f32_e32 v8, v8, v25
	v_cndmask_b32_e64 v2, v2, v74, s[22:23]
	v_add_f32_e32 v8, v8, v21
	s_waitcnt vmcnt(0)
	v_lshlrev_b32_e32 v61, 16, v135
	v_add_f32_e32 v8, v8, v2
	v_add_f32_e32 v8, v8, v61
	v_sub_f32_e32 v1, v1, v57
	v_div_scale_f32 v22, s[0:1], v6, v6, v8
	v_add_f32_e32 v1, v1, v137
	s_mov_b32 s2, 0x3d800000
	v_rcp_f32_e32 v23, v22
	v_fma_f32 v1, v1, s2, -v137
	v_bfe_u32 v26, v1, 16, 1
	v_add3_u32 v1, v1, v26, s33
	ds_write_b16_d16_hi v101, v1 offset:4080
	v_fma_f32 v1, -v22, v23, 1.0
	v_fmac_f32_e32 v23, v1, v23
	v_div_scale_f32 v1, vcc, v8, v6, v8
	v_mul_f32_e32 v26, v1, v23
	v_fma_f32 v29, -v22, v26, v1
	v_fmac_f32_e32 v26, v29, v23
	v_fma_f32 v1, -v22, v26, v1
	v_div_fmas_f32 v1, v1, v23, v26
	v_lshlrev_b32_e32 v60, 16, v133
	v_div_fixup_f32 v1, v1, v6, v8
	v_sub_f32_e32 v6, v8, v56
	v_add_f32_e32 v6, v6, v60
	v_div_scale_f32 v8, s[0:1], v5, v5, v6
	v_rcp_f32_e32 v22, v8
	v_sub_f32_e32 v1, v1, v61
	v_bfe_u32 v23, v1, 16, 1
	v_add3_u32 v1, v1, v23, s33
	ds_write_b16_d16_hi v101, v1 offset:128
	v_fma_f32 v1, -v8, v22, 1.0
	v_fmac_f32_e32 v22, v1, v22
	v_div_scale_f32 v1, vcc, v6, v5, v6
	v_mul_f32_e32 v23, v1, v22
	v_fma_f32 v26, -v8, v23, v1
	v_fmac_f32_e32 v23, v26, v22
	v_fma_f32 v1, -v8, v23, v1
	v_div_fmas_f32 v1, v1, v22, v23
	v_lshlrev_b32_e32 v54, 16, v90
	v_div_fixup_f32 v1, v1, v5, v6
	v_sub_f32_e32 v5, v6, v55
	v_add_f32_e32 v5, v5, v54
	v_div_scale_f32 v6, s[0:1], v4, v4, v5
	v_rcp_f32_e32 v8, v6
	v_sub_f32_e32 v1, v1, v60
	v_bfe_u32 v22, v1, 16, 1
	v_add3_u32 v1, v1, v22, s33
	ds_write_b16_d16_hi v101, v1 offset:400
	v_fma_f32 v1, -v6, v8, 1.0
	v_fmac_f32_e32 v8, v1, v8
	v_div_scale_f32 v1, vcc, v5, v4, v5
	v_mul_f32_e32 v22, v1, v8
	v_fma_f32 v23, -v6, v22, v1
	v_fmac_f32_e32 v22, v23, v8
	v_fma_f32 v1, -v6, v22, v1
	v_div_fmas_f32 v1, v1, v8, v22
	v_lshlrev_b32_e32 v52, 16, v89
	v_div_fixup_f32 v1, v1, v4, v5
	v_sub_f32_e32 v4, v5, v53
	v_add_f32_e32 v4, v4, v52
	v_div_scale_f32 v5, s[0:1], v7, v7, v4
	v_rcp_f32_e32 v6, v5
	v_sub_f32_e32 v1, v1, v54
	v_bfe_u32 v8, v1, 16, 1
	v_add3_u32 v1, v1, v8, s33
	ds_write_b16_d16_hi v101, v1 offset:672
	v_fma_f32 v1, -v5, v6, 1.0
	v_fmac_f32_e32 v6, v1, v6
	v_div_scale_f32 v1, vcc, v4, v7, v4
	v_mul_f32_e32 v8, v1, v6
	v_fma_f32 v22, -v5, v8, v1
	v_fmac_f32_e32 v8, v22, v6
	v_fma_f32 v1, -v5, v8, v1
	v_div_fmas_f32 v1, v1, v6, v8
	v_lshlrev_b32_e32 v47, 16, v88
	v_div_fixup_f32 v1, v1, v7, v4
	v_sub_f32_e32 v4, v4, v48
	v_add_f32_e32 v4, v4, v47
	v_div_scale_f32 v5, s[0:1], v9, v9, v4
	v_rcp_f32_e32 v6, v5
	v_sub_f32_e32 v1, v1, v52
	v_bfe_u32 v7, v1, 16, 1
	v_add3_u32 v1, v1, v7, s33
	ds_write_b16_d16_hi v101, v1 offset:944
	v_fma_f32 v1, -v5, v6, 1.0
	v_fmac_f32_e32 v6, v1, v6
	v_div_scale_f32 v1, vcc, v4, v9, v4
	v_mul_f32_e32 v7, v1, v6
	v_fma_f32 v8, -v5, v7, v1
	v_fmac_f32_e32 v7, v8, v6
	v_fma_f32 v1, -v5, v7, v1
	v_div_fmas_f32 v1, v1, v6, v7
	v_lshlrev_b32_e32 v45, 16, v87
	v_div_fixup_f32 v1, v1, v9, v4
	v_sub_f32_e32 v4, v4, v46
	v_add_f32_e32 v4, v4, v45
	v_div_scale_f32 v5, s[0:1], v10, v10, v4
	v_rcp_f32_e32 v6, v5
	v_sub_f32_e32 v1, v1, v47
	v_bfe_u32 v7, v1, 16, 1
	v_add3_u32 v1, v1, v7, s33
	ds_write_b16_d16_hi v101, v1 offset:1216
	v_fma_f32 v1, -v5, v6, 1.0
	v_fmac_f32_e32 v6, v1, v6
	v_div_scale_f32 v1, vcc, v4, v10, v4
	v_mul_f32_e32 v7, v1, v6
	v_fma_f32 v8, -v5, v7, v1
	v_fmac_f32_e32 v7, v8, v6
	v_fma_f32 v1, -v5, v7, v1
	v_div_fmas_f32 v1, v1, v6, v7
	v_lshlrev_b32_e32 v43, 16, v86
	v_div_fixup_f32 v1, v1, v10, v4
	v_sub_f32_e32 v4, v4, v44
	v_add_f32_e32 v4, v4, v43
	v_div_scale_f32 v5, s[0:1], v11, v11, v4
	v_rcp_f32_e32 v6, v5
	v_sub_f32_e32 v1, v1, v45
	v_bfe_u32 v7, v1, 16, 1
	v_add3_u32 v1, v1, v7, s33
	ds_write_b16_d16_hi v101, v1 offset:1488
	v_fma_f32 v1, -v5, v6, 1.0
	v_fmac_f32_e32 v6, v1, v6
	v_div_scale_f32 v1, vcc, v4, v11, v4
	v_mul_f32_e32 v7, v1, v6
	v_fma_f32 v8, -v5, v7, v1
	v_fmac_f32_e32 v7, v8, v6
	v_fma_f32 v1, -v5, v7, v1
	v_div_fmas_f32 v1, v1, v6, v7
	v_lshlrev_b32_e32 v41, 16, v85
	v_div_fixup_f32 v1, v1, v11, v4
	v_sub_f32_e32 v4, v4, v42
	v_add_f32_e32 v4, v4, v41
	v_div_scale_f32 v5, s[0:1], v12, v12, v4
	v_rcp_f32_e32 v6, v5
	v_sub_f32_e32 v1, v1, v43
	v_bfe_u32 v7, v1, 16, 1
	v_add3_u32 v1, v1, v7, s33
	ds_write_b16_d16_hi v101, v1 offset:1760
	v_fma_f32 v1, -v5, v6, 1.0
	v_fmac_f32_e32 v6, v1, v6
	v_div_scale_f32 v1, vcc, v4, v12, v4
	v_mul_f32_e32 v7, v1, v6
	v_fma_f32 v8, -v5, v7, v1
	v_fmac_f32_e32 v7, v8, v6
	v_fma_f32 v1, -v5, v7, v1
	v_div_fmas_f32 v1, v1, v6, v7
	v_lshlrev_b32_e32 v39, 16, v84
	v_div_fixup_f32 v1, v1, v12, v4
	v_sub_f32_e32 v4, v4, v40
	v_add_f32_e32 v4, v4, v39
	v_div_scale_f32 v5, s[0:1], v13, v13, v4
	v_rcp_f32_e32 v6, v5
	v_sub_f32_e32 v1, v1, v41
	v_bfe_u32 v7, v1, 16, 1
	v_add3_u32 v1, v1, v7, s33
	ds_write_b16_d16_hi v101, v1 offset:2032
	v_fma_f32 v1, -v5, v6, 1.0
	v_fmac_f32_e32 v6, v1, v6
	v_div_scale_f32 v1, vcc, v4, v13, v4
	v_mul_f32_e32 v7, v1, v6
	v_fma_f32 v8, -v5, v7, v1
	v_fmac_f32_e32 v7, v8, v6
	v_fma_f32 v1, -v5, v7, v1
	v_div_fmas_f32 v1, v1, v6, v7
	v_lshlrev_b32_e32 v37, 16, v83
	v_div_fixup_f32 v1, v1, v13, v4
	v_sub_f32_e32 v4, v4, v38
	v_add_f32_e32 v4, v4, v37
	v_div_scale_f32 v5, s[0:1], v14, v14, v4
	v_rcp_f32_e32 v6, v5
	v_sub_f32_e32 v1, v1, v39
	v_bfe_u32 v7, v1, 16, 1
	v_add3_u32 v1, v1, v7, s33
	ds_write_b16_d16_hi v101, v1 offset:2304
	v_fma_f32 v1, -v5, v6, 1.0
	v_fmac_f32_e32 v6, v1, v6
	v_div_scale_f32 v1, vcc, v4, v14, v4
	v_mul_f32_e32 v7, v1, v6
	v_fma_f32 v8, -v5, v7, v1
	v_fmac_f32_e32 v7, v8, v6
	v_fma_f32 v1, -v5, v7, v1
	v_div_fmas_f32 v1, v1, v6, v7
	v_lshlrev_b32_e32 v35, 16, v82
	v_div_fixup_f32 v1, v1, v14, v4
	v_sub_f32_e32 v4, v4, v36
	v_add_f32_e32 v4, v4, v35
	v_div_scale_f32 v5, s[0:1], v15, v15, v4
	v_rcp_f32_e32 v6, v5
	v_sub_f32_e32 v1, v1, v37
	v_bfe_u32 v7, v1, 16, 1
	v_add3_u32 v1, v1, v7, s33
	ds_write_b16_d16_hi v101, v1 offset:2576
	v_fma_f32 v1, -v5, v6, 1.0
	v_fmac_f32_e32 v6, v1, v6
	v_div_scale_f32 v1, vcc, v4, v15, v4
	v_mul_f32_e32 v7, v1, v6
	v_fma_f32 v8, -v5, v7, v1
	v_fmac_f32_e32 v7, v8, v6
	v_fma_f32 v1, -v5, v7, v1
	v_div_fmas_f32 v1, v1, v6, v7
	v_lshlrev_b32_e32 v30, 16, v81
	v_div_fixup_f32 v1, v1, v15, v4
	v_sub_f32_e32 v4, v4, v33
	v_add_f32_e32 v4, v4, v30
	v_div_scale_f32 v5, s[0:1], v16, v16, v4
	v_rcp_f32_e32 v6, v5
	v_sub_f32_e32 v1, v1, v35
	v_bfe_u32 v7, v1, 16, 1
	v_add3_u32 v1, v1, v7, s33
	ds_write_b16_d16_hi v101, v1 offset:2848
	v_fma_f32 v1, -v5, v6, 1.0
	v_fmac_f32_e32 v6, v1, v6
	v_div_scale_f32 v1, vcc, v4, v16, v4
	v_mul_f32_e32 v7, v1, v6
	v_fma_f32 v8, -v5, v7, v1
	v_fmac_f32_e32 v7, v8, v6
	v_fma_f32 v1, -v5, v7, v1
	v_div_fmas_f32 v1, v1, v6, v7
	v_lshlrev_b32_e32 v27, 16, v80
	v_div_fixup_f32 v1, v1, v16, v4
	v_sub_f32_e32 v4, v4, v28
	v_add_f32_e32 v4, v4, v27
	v_div_scale_f32 v5, s[0:1], v17, v17, v4
	v_rcp_f32_e32 v6, v5
	v_sub_f32_e32 v1, v1, v30
	v_bfe_u32 v7, v1, 16, 1
	v_add3_u32 v1, v1, v7, s33
	ds_write_b16_d16_hi v101, v1 offset:3120
	v_fma_f32 v1, -v5, v6, 1.0
	v_fmac_f32_e32 v6, v1, v6
	v_div_scale_f32 v1, vcc, v4, v17, v4
	v_mul_f32_e32 v7, v1, v6
	v_fma_f32 v8, -v5, v7, v1
	v_fmac_f32_e32 v7, v8, v6
	v_fma_f32 v1, -v5, v7, v1
	v_div_fmas_f32 v1, v1, v6, v7
	v_lshlrev_b32_e32 v24, 16, v79
	v_div_fixup_f32 v1, v1, v17, v4
	v_sub_f32_e32 v4, v4, v25
	v_add_f32_e32 v4, v4, v24
	v_div_scale_f32 v5, s[0:1], v18, v18, v4
	v_rcp_f32_e32 v6, v5
	v_sub_f32_e32 v1, v1, v27
	v_bfe_u32 v7, v1, 16, 1
	v_add3_u32 v1, v1, v7, s33
	ds_write_b16_d16_hi v101, v1 offset:3392
	v_fma_f32 v1, -v5, v6, 1.0
	v_fmac_f32_e32 v6, v1, v6
	v_div_scale_f32 v1, vcc, v4, v18, v4
	v_mul_f32_e32 v7, v1, v6
	v_fma_f32 v8, -v5, v7, v1
	v_fmac_f32_e32 v7, v8, v6
	v_fma_f32 v1, -v5, v7, v1
	v_div_fmas_f32 v1, v1, v6, v7
	v_lshlrev_b32_e32 v20, 16, v78
	v_div_fixup_f32 v1, v1, v18, v4
	v_sub_f32_e32 v4, v4, v21
	v_add_f32_e32 v4, v4, v20
	v_div_scale_f32 v5, s[0:1], v19, v19, v4
	v_rcp_f32_e32 v6, v5
	v_sub_f32_e32 v1, v1, v24
	v_bfe_u32 v7, v1, 16, 1
	v_add3_u32 v1, v1, v7, s33
	ds_write_b16_d16_hi v101, v1 offset:3664
	v_fma_f32 v1, -v5, v6, 1.0
	v_fmac_f32_e32 v6, v1, v6
	v_div_scale_f32 v1, vcc, v4, v19, v4
	v_mul_f32_e32 v7, v1, v6
	v_fma_f32 v8, -v5, v7, v1
	v_fmac_f32_e32 v7, v8, v6
	v_fma_f32 v1, -v5, v7, v1
	v_div_fmas_f32 v1, v1, v6, v7
	v_div_fixup_f32 v1, v1, v19, v4
	v_sub_f32_e32 v1, v1, v20
	v_bfe_u32 v5, v1, 16, 1
	v_add3_u32 v1, v1, v5, s33
	v_lshlrev_b32_e32 v3, 16, v3
	ds_write_b16_d16_hi v101, v1 offset:3936
	v_sub_f32_e32 v1, v4, v2
	v_add_f32_e32 v1, v1, v3
	v_fma_f32 v1, v1, s2, -v3
	v_bfe_u32 v2, v1, 16, 1
	v_add3_u32 v1, v1, v2, s33
	ds_write_b16_d16_hi v101, v1 offset:4208
	v_mov_b64_e32 v[78:79], v[96:97]
	ds_read_b128 v[6:9], v105
	ds_read_b128 v[10:13], v105 offset:64
	ds_read_b128 v[14:17], v105 offset:128
	ds_read_b128 v[2:5], v105 offset:192
	v_or_b32_e32 v90, s19, v94
	v_readlane_b32 s72, v251, 52
	v_readlane_b32 s74, v251, 54
	v_readlane_b32 s70, v251, 58
	v_readlane_b32 s68, v251, 60
	v_readlane_b32 s34, v250, 0
	s_mov_b64 s[0:1], 0
	v_readlane_b32 s73, v251, 53
	v_readlane_b32 s75, v251, 55
	v_readlane_b32 s71, v251, 59
	v_readlane_b32 s69, v251, 61
	v_readlane_b32 s35, v250, 1
	s_mov_b64 s[36:37], 0x8000
	s_mov_b64 s[38:39], 0x8080
	s_mov_b64 s[40:41], 0xc400
	global_load_dwordx4 v[18:21], v[78:79], off
	global_load_dwordx4 v[22:25], v[78:79], off offset:64
	global_load_dwordx4 v[26:29], v[78:79], off offset:128
	global_load_dwordx4 v[30:33], v[78:79], off offset:192
	v_add_co_u32_e32 v78, vcc, 0x1000, v78
	s_nop 1
	v_addc_co_u32_e32 v79, vcc, 0, v79, vcc
	global_load_dwordx4 v[34:37], v[78:79], off
	global_load_dwordx4 v[38:41], v[78:79], off offset:64
	global_load_dwordx4 v[42:45], v[78:79], off offset:128
	global_load_dwordx4 v[46:49], v[78:79], off offset:192
	v_add_co_u32_e32 v78, vcc, 0x1000, v78
	s_nop 1
	v_addc_co_u32_e32 v79, vcc, 0, v79, vcc
	global_load_dwordx4 v[50:53], v[78:79], off
	global_load_dwordx4 v[54:57], v[78:79], off offset:64
	global_load_dwordx4 v[58:61], v[78:79], off offset:128
	global_load_dwordx4 v[62:65], v[78:79], off offset:192
	v_add_co_u32_e32 v78, vcc, 0x1000, v78
	s_nop 1
	v_addc_co_u32_e32 v79, vcc, 0, v79, vcc
	global_load_dwordx4 v[66:69], v[78:79], off
	global_load_dwordx4 v[70:73], v[78:79], off offset:64
	global_load_dwordx4 v[74:77], v[78:79], off offset:128
	global_load_dwordx4 v[240:243], v[78:79], off offset:192
	v_add_co_u32_e32 v78, vcc, 0x1000, v78
	s_nop 1
	v_addc_co_u32_e32 v79, vcc, 0, v79, vcc
	global_load_dwordx4 v[174:177], v[78:79], off
	global_load_dwordx4 v[178:181], v[78:79], off offset:64
	global_load_dwordx4 v[182:185], v[78:79], off offset:128
	global_load_dwordx4 v[186:189], v[78:79], off offset:192
	v_add_co_u32_e32 v78, vcc, 0x1000, v78
	s_nop 1
	v_addc_co_u32_e32 v79, vcc, 0, v79, vcc
	global_load_dwordx4 v[190:193], v[78:79], off
	global_load_dwordx4 v[194:197], v[78:79], off offset:64
	global_load_dwordx4 v[198:201], v[78:79], off offset:128
	global_load_dwordx4 v[202:205], v[78:79], off offset:192
	v_add_co_u32_e32 v78, vcc, 0x1000, v78
	s_nop 1
	v_addc_co_u32_e32 v79, vcc, 0, v79, vcc
	global_load_dwordx4 v[206:209], v[78:79], off
	global_load_dwordx4 v[210:213], v[78:79], off offset:64
	global_load_dwordx4 v[214:217], v[78:79], off offset:128
	global_load_dwordx4 v[218:221], v[78:79], off offset:192
	v_add_co_u32_e32 v78, vcc, 0x1000, v78
	s_nop 1
	v_addc_co_u32_e32 v79, vcc, 0, v79, vcc
	global_load_dwordx4 v[222:225], v[78:79], off
	global_load_dwordx4 v[226:229], v[78:79], off offset:64
	global_load_dwordx4 v[230:233], v[78:79], off offset:128
	global_load_dwordx4 v[234:237], v[78:79], off offset:192
	v_lshlrev_b64 v[244:245], 11, v[90:91]
	v_lshl_add_u64 v[244:245], v[120:121], 0, v[244:245]
	s_waitcnt lgkmcnt(0)
	s_waitcnt vmcnt(28)
	v_mfma_f32_16x16x32_bf16 v[18:21], v[18:21], v[6:9], 0
	v_mfma_f32_16x16x32_bf16 v[18:21], v[22:25], v[10:13], v[18:21]
	v_mfma_f32_16x16x32_bf16 v[18:21], v[26:29], v[14:17], v[18:21]
	v_mfma_f32_16x16x32_bf16 v[18:21], v[30:33], v[2:5], v[18:21]
	s_waitcnt vmcnt(24)
	v_mfma_f32_16x16x32_bf16 v[34:37], v[34:37], v[6:9], 0
	v_mfma_f32_16x16x32_bf16 v[34:37], v[38:41], v[10:13], v[34:37]
	v_mfma_f32_16x16x32_bf16 v[34:37], v[42:45], v[14:17], v[34:37]
	v_mfma_f32_16x16x32_bf16 v[34:37], v[46:49], v[2:5], v[34:37]
	global_load_dwordx4 v[22:25], v[126:127], off offset:1536
	global_load_dwordx4 v[26:29], v[126:127], off offset:1600
	global_load_dwordx4 v[30:33], v[126:127], off offset:1664
	s_waitcnt vmcnt(23)
	v_mfma_f32_16x16x32_bf16 v[50:53], v[50:53], v[6:9], 0
	v_mfma_f32_16x16x32_bf16 v[50:53], v[54:57], v[10:13], v[50:53]
	v_mfma_f32_16x16x32_bf16 v[50:53], v[58:61], v[14:17], v[50:53]
	v_mfma_f32_16x16x32_bf16 v[50:53], v[62:65], v[2:5], v[50:53]
	global_load_dwordx4 v[38:41], v[126:127], off offset:1728
	global_load_dwordx4 v[42:45], v[126:127], off offset:1792
	global_load_dwordx4 v[46:49], v[126:127], off offset:1856
	s_waitcnt vmcnt(22)
	v_mfma_f32_16x16x32_bf16 v[66:69], v[66:69], v[6:9], 0
	v_mfma_f32_16x16x32_bf16 v[66:69], v[70:73], v[10:13], v[66:69]
	v_mfma_f32_16x16x32_bf16 v[66:69], v[74:77], v[14:17], v[66:69]
	v_mfma_f32_16x16x32_bf16 v[66:69], v[240:243], v[2:5], v[66:69]
	global_load_dwordx4 v[54:57], v[126:127], off offset:1920
	global_load_dwordx4 v[58:61], v[126:127], off offset:1984
	s_waitcnt vmcnt(20)
	v_mfma_f32_16x16x32_bf16 v[174:177], v[174:177], v[6:9], 0
	v_mfma_f32_16x16x32_bf16 v[174:177], v[178:181], v[10:13], v[174:177]
	v_mfma_f32_16x16x32_bf16 v[174:177], v[182:185], v[14:17], v[174:177]
	v_mfma_f32_16x16x32_bf16 v[174:177], v[186:189], v[2:5], v[174:177]
	s_waitcnt vmcnt(16)
	v_mfma_f32_16x16x32_bf16 v[190:193], v[190:193], v[6:9], 0
	v_mfma_f32_16x16x32_bf16 v[190:193], v[194:197], v[10:13], v[190:193]
	v_mfma_f32_16x16x32_bf16 v[190:193], v[198:201], v[14:17], v[190:193]
	v_mfma_f32_16x16x32_bf16 v[190:193], v[202:205], v[2:5], v[190:193]
	s_waitcnt vmcnt(12)
	v_mfma_f32_16x16x32_bf16 v[206:209], v[206:209], v[6:9], 0
	v_mfma_f32_16x16x32_bf16 v[206:209], v[210:213], v[10:13], v[206:209]
	v_mfma_f32_16x16x32_bf16 v[206:209], v[214:217], v[14:17], v[206:209]
	v_mfma_f32_16x16x32_bf16 v[206:209], v[218:221], v[2:5], v[206:209]
	s_waitcnt vmcnt(8)
	v_mfma_f32_16x16x32_bf16 v[222:225], v[222:225], v[6:9], 0
	v_mfma_f32_16x16x32_bf16 v[222:225], v[226:229], v[10:13], v[222:225]
	v_mfma_f32_16x16x32_bf16 v[222:225], v[230:233], v[14:17], v[222:225]
	v_mfma_f32_16x16x32_bf16 v[222:225], v[234:237], v[2:5], v[222:225]
	s_nop 7
	s_waitcnt vmcnt(5)
	v_pk_mul_f32 v[18:19], v[18:19], v[22:23]
	v_pk_mul_f32 v[20:21], v[20:21], v[24:25]
	v_cvt_pk_bf16_f32 v18, v18, v19
	v_cvt_pk_bf16_f32 v19, v20, v21
	global_store_dwordx2 v[244:245], v[18:19], off offset:1792
	v_pk_mul_f32 v[34:35], v[34:35], v[26:27]
	v_pk_mul_f32 v[36:37], v[36:37], v[28:29]
	v_cvt_pk_bf16_f32 v34, v34, v35
	v_cvt_pk_bf16_f32 v35, v36, v37
	global_store_dwordx2 v[244:245], v[34:35], off offset:1824
	v_pk_mul_f32 v[50:51], v[50:51], v[30:31]
	v_pk_mul_f32 v[52:53], v[52:53], v[32:33]
	v_cvt_pk_bf16_f32 v50, v50, v51
	v_cvt_pk_bf16_f32 v51, v52, v53
	global_store_dwordx2 v[244:245], v[50:51], off offset:1856
	s_waitcnt vmcnt(2)
	v_pk_mul_f32 v[66:67], v[66:67], v[38:39]
	v_pk_mul_f32 v[68:69], v[68:69], v[40:41]
	v_cvt_pk_bf16_f32 v66, v66, v67
	v_cvt_pk_bf16_f32 v67, v68, v69
	global_store_dwordx2 v[244:245], v[66:67], off offset:1888
	v_pk_mul_f32 v[174:175], v[174:175], v[42:43]
	v_pk_mul_f32 v[176:177], v[176:177], v[44:45]
	v_cvt_pk_bf16_f32 v174, v174, v175
	v_cvt_pk_bf16_f32 v175, v176, v177
	global_store_dwordx2 v[244:245], v[174:175], off offset:1920
	v_pk_mul_f32 v[190:191], v[190:191], v[46:47]
	v_pk_mul_f32 v[192:193], v[192:193], v[48:49]
	v_cvt_pk_bf16_f32 v190, v190, v191
	v_cvt_pk_bf16_f32 v191, v192, v193
	global_store_dwordx2 v[244:245], v[190:191], off offset:1952
	s_waitcnt vmcnt(0)
	v_pk_mul_f32 v[206:207], v[206:207], v[54:55]
	v_pk_mul_f32 v[208:209], v[208:209], v[56:57]
	v_cvt_pk_bf16_f32 v206, v206, v207
	v_cvt_pk_bf16_f32 v207, v208, v209
	global_store_dwordx2 v[244:245], v[206:207], off offset:1984
	v_pk_mul_f32 v[222:223], v[222:223], v[58:59]
	v_pk_mul_f32 v[224:225], v[224:225], v[60:61]
	v_cvt_pk_bf16_f32 v222, v222, v223
	v_cvt_pk_bf16_f32 v223, v224, v225
	global_store_dwordx2 v[244:245], v[222:223], off offset:2016

.LBB0_787:
	s_nop 0
	global_load_ushort v2, v39, s[78:79]
	global_load_ushort v3, v39, s[74:75]
	global_load_ushort v5, v39, s[72:73]
	global_load_ushort v49, v39, s[70:71]
	global_load_ushort v50, v39, s[68:69]
	global_load_ushort v51, v39, s[66:67]
	global_load_ushort v52, v39, s[60:61]
	global_load_ushort v53, v39, s[10:11]
	global_load_ushort v54, v39, s[58:59]
	global_load_ushort v55, v39, s[56:57]
	global_load_ushort v56, v39, s[50:51]
	global_load_ushort v57, v39, s[48:49]
	global_load_ushort v58, v39, s[46:47]
	global_load_ushort v59, v39, s[42:43]
	global_load_ushort v60, v39, s[40:41]
	s_nop 0
	global_load_ushort v39, v39, s[34:35]
	s_waitcnt vmcnt(0)
	v_lshlrev_b32_e32 v1, 16, v1
	v_lshlrev_b32_e32 v10, 16, v10
	v_cndmask_b32_e64 v1, v1, v9, s[22:23]
	v_lshlrev_b32_e32 v13, 16, v13
	v_cndmask_b32_e64 v8, v10, v8, s[22:23]
	v_add_f32_e32 v9, 0, v1
	v_lshlrev_b32_e32 v14, 16, v14
	v_cndmask_b32_e64 v12, v13, v12, s[22:23]
	v_add_f32_e32 v9, v9, v8
	v_lshlrev_b32_e32 v17, 16, v17
	v_cndmask_b32_e64 v11, v14, v11, s[22:23]
	v_add_f32_e32 v9, v9, v12
	v_lshlrev_b32_e32 v18, 16, v18
	v_cndmask_b32_e64 v16, v17, v16, s[22:23]
	v_add_f32_e32 v9, v9, v11
	v_lshlrev_b32_e32 v22, 16, v22
	s_add_i32 s0, s12, s36
	v_cndmask_b32_e64 v15, v18, v15, s[22:23]
	v_add_f32_e32 v9, v9, v16
	v_cndmask_b32_e64 v20, v22, v20, s[22:23]
	v_add_f32_e32 v9, v9, v15
	s_min_u32 s1, s0, 7
	v_lshlrev_b32_e32 v4, 16, v4
	v_lshlrev_b32_e32 v48, 16, v48
	v_lshlrev_b32_e32 v24, 16, v24
	v_add_f32_e32 v9, v9, v20
	s_add_i32 s1, s1, 1
	v_cndmask_b32_e64 v4, v4, v45, s[22:23]
	v_cndmask_b32_e64 v45, v48, v46, s[22:23]
	v_add_f32_e32 v9, v9, v24
	v_cvt_f32_ubyte0_e32 v48, s1
	s_or_b32 s1, s0, 1
	s_min_u32 s1, s1, 7
	v_lshlrev_b32_e32 v6, 16, v6
	v_sub_f32_e32 v1, v9, v1
	s_add_i32 s1, s1, 1
	v_add_f32_e32 v1, v1, v6
	v_lshlrev_b32_e32 v7, 16, v7
	v_lshlrev_b32_e32 v23, 16, v23
	v_lshlrev_b32_e32 v25, 16, v25
	v_lshlrev_b32_e32 v26, 16, v26
	v_lshlrev_b32_e32 v27, 16, v27
	v_lshlrev_b32_e32 v28, 16, v28
	v_lshlrev_b32_e32 v29, 16, v29
	v_lshlrev_b32_e32 v30, 16, v30
	v_lshlrev_b32_e32 v31, 16, v31
	v_lshlrev_b32_e32 v32, 16, v32
	v_lshlrev_b32_e32 v33, 16, v33
	v_lshlrev_b32_e32 v34, 16, v34
	v_lshlrev_b32_e32 v35, 16, v35
	v_lshlrev_b32_e32 v38, 16, v38
	v_lshlrev_b32_e32 v40, 16, v40
	v_cndmask_b32_e64 v19, v38, v19, s[22:23]
	v_lshlrev_b32_e32 v43, 16, v43
	v_cndmask_b32_e64 v37, v40, v37, s[22:23]
	v_lshlrev_b32_e32 v44, 16, v44
	v_cndmask_b32_e64 v36, v43, v36, s[22:23]
	v_lshlrev_b32_e32 v47, 16, v47
	v_cndmask_b32_e64 v42, v44, v42, s[22:23]
	v_cndmask_b32_e64 v41, v47, v41, s[22:23]
	v_lshlrev_b32_e32 v21, 16, v21
	v_mov_b64_e32 v[78:79], v[102:103]
	v_or_b32_e32 v90, s19, v94
	v_readlane_b32 s72, v251, 52
	v_lshlrev_b32_e32 v2, 16, v2
	v_lshlrev_b32_e32 v3, 16, v3
	v_lshlrev_b32_e32 v5, 16, v5
	v_lshlrev_b32_e32 v10, 16, v49
	v_div_scale_f32 v49, s[2:3], v48, v48, v9
	v_lshlrev_b32_e32 v13, 16, v50
	v_rcp_f32_e32 v50, v49
	v_lshlrev_b32_e32 v14, 16, v51
	v_lshlrev_b32_e32 v17, 16, v52
	v_lshlrev_b32_e32 v18, 16, v53
	v_fma_f32 v51, -v49, v50, 1.0
	v_fmac_f32_e32 v50, v51, v50
	v_div_scale_f32 v51, vcc, v9, v48, v9
	v_mul_f32_e32 v52, v51, v50
	v_fma_f32 v53, -v49, v52, v51
	v_fmac_f32_e32 v52, v53, v50
	v_fma_f32 v49, -v49, v52, v51
	v_div_fmas_f32 v49, v49, v50, v52
	v_div_fixup_f32 v49, v49, v48, v9
	v_cvt_f32_ubyte0_e32 v9, s1
	v_div_scale_f32 v50, s[2:3], v9, v9, v1
	v_rcp_f32_e32 v51, v50
	v_sub_f32_e32 v49, v49, v24
	v_bfe_u32 v52, v49, 16, 1
	v_add3_u32 v49, v49, v52, s33
	ds_write_b16_d16_hi v101, v49
	v_fma_f32 v49, -v50, v51, 1.0
	v_fmac_f32_e32 v51, v49, v51
	v_div_scale_f32 v49, vcc, v1, v9, v1
	v_mul_f32_e32 v52, v49, v51
	v_fma_f32 v53, -v50, v52, v49
	v_fmac_f32_e32 v52, v53, v51
	v_fma_f32 v49, -v50, v52, v49
	s_or_b32 s1, s0, 2
	v_div_fmas_f32 v49, v49, v51, v52
	s_min_u32 s1, s1, 7
	v_div_fixup_f32 v49, v49, v9, v1
	v_sub_f32_e32 v1, v1, v8
	s_add_i32 s1, s1, 1
	v_add_f32_e32 v1, v1, v7
	v_cvt_f32_ubyte0_e32 v8, s1
	v_div_scale_f32 v50, s[2:3], v8, v8, v1
	v_rcp_f32_e32 v51, v50
	v_sub_f32_e32 v49, v49, v6
	v_bfe_u32 v52, v49, 16, 1
	v_add3_u32 v49, v49, v52, s33
	ds_write_b16_d16_hi v101, v49 offset:272
	v_fma_f32 v49, -v50, v51, 1.0
	v_fmac_f32_e32 v51, v49, v51
	v_div_scale_f32 v49, vcc, v1, v8, v1
	v_mul_f32_e32 v52, v49, v51
	v_fma_f32 v53, -v50, v52, v49
	v_fmac_f32_e32 v52, v53, v51
	v_fma_f32 v49, -v50, v52, v49
	s_or_b32 s1, s0, 3
	v_div_fmas_f32 v49, v49, v51, v52
	s_min_u32 s1, s1, 7
	v_div_fixup_f32 v49, v49, v8, v1
	v_sub_f32_e32 v1, v1, v12
	s_add_i32 s1, s1, 1
	v_add_f32_e32 v1, v1, v23
	v_cvt_f32_ubyte0_e32 v12, s1
	v_div_scale_f32 v50, s[2:3], v12, v12, v1
	v_rcp_f32_e32 v51, v50
	v_sub_f32_e32 v49, v49, v7
	v_bfe_u32 v52, v49, 16, 1
	v_add3_u32 v49, v49, v52, s33
	ds_write_b16_d16_hi v101, v49 offset:544
	v_fma_f32 v49, -v50, v51, 1.0
	v_fmac_f32_e32 v51, v49, v51
	v_div_scale_f32 v49, vcc, v1, v12, v1
	v_mul_f32_e32 v52, v49, v51
	v_fma_f32 v53, -v50, v52, v49
	v_fmac_f32_e32 v52, v53, v51
	v_fma_f32 v49, -v50, v52, v49
	s_or_b32 s1, s0, 4
	v_div_fmas_f32 v49, v49, v51, v52
	s_min_u32 s1, s1, 7
	v_div_fixup_f32 v49, v49, v12, v1
	v_sub_f32_e32 v1, v1, v11
	s_add_i32 s1, s1, 1
	v_add_f32_e32 v1, v1, v25
	v_cvt_f32_ubyte0_e32 v11, s1
	v_div_scale_f32 v50, s[2:3], v11, v11, v1
	v_rcp_f32_e32 v51, v50
	v_sub_f32_e32 v49, v49, v23
	v_bfe_u32 v52, v49, 16, 1
	v_add3_u32 v49, v49, v52, s33
	ds_write_b16_d16_hi v101, v49 offset:816
	v_fma_f32 v49, -v50, v51, 1.0
	v_fmac_f32_e32 v51, v49, v51
	v_div_scale_f32 v49, vcc, v1, v11, v1
	v_mul_f32_e32 v52, v49, v51
	v_fma_f32 v53, -v50, v52, v49
	v_fmac_f32_e32 v52, v53, v51
	v_fma_f32 v49, -v50, v52, v49
	s_or_b32 s1, s0, 5
	v_div_fmas_f32 v49, v49, v51, v52
	s_min_u32 s1, s1, 7
	v_div_fixup_f32 v49, v49, v11, v1
	v_sub_f32_e32 v1, v1, v16
	s_add_i32 s1, s1, 1
	v_add_f32_e32 v1, v1, v26
	v_cvt_f32_ubyte0_e32 v16, s1
	v_div_scale_f32 v50, s[2:3], v16, v16, v1
	v_rcp_f32_e32 v51, v50
	v_sub_f32_e32 v49, v49, v25
	v_bfe_u32 v52, v49, 16, 1
	v_add3_u32 v49, v49, v52, s33
	ds_write_b16_d16_hi v101, v49 offset:1088
	v_fma_f32 v49, -v50, v51, 1.0
	v_fmac_f32_e32 v51, v49, v51
	v_div_scale_f32 v49, vcc, v1, v16, v1
	v_mul_f32_e32 v52, v49, v51
	v_fma_f32 v53, -v50, v52, v49
	v_fmac_f32_e32 v52, v53, v51
	v_fma_f32 v49, -v50, v52, v49
	s_or_b32 s0, s0, 6
	v_div_fmas_f32 v49, v49, v51, v52
	s_min_u32 s0, s0, 7
	v_div_fixup_f32 v49, v49, v16, v1
	v_sub_f32_e32 v1, v1, v15
	s_add_i32 s0, s0, 1
	v_add_f32_e32 v1, v1, v27
	v_cvt_f32_ubyte0_e32 v15, s0
	v_div_scale_f32 v50, s[0:1], v15, v15, v1
	v_rcp_f32_e32 v51, v50
	v_sub_f32_e32 v49, v49, v26
	v_bfe_u32 v52, v49, 16, 1
	v_add3_u32 v49, v49, v52, s33
	ds_write_b16_d16_hi v101, v49 offset:1360
	v_fma_f32 v49, -v50, v51, 1.0
	v_fmac_f32_e32 v51, v49, v51
	v_div_scale_f32 v49, vcc, v1, v15, v1
	v_mul_f32_e32 v52, v49, v51
	v_fma_f32 v53, -v50, v52, v49
	v_fmac_f32_e32 v52, v53, v51
	v_fma_f32 v49, -v50, v52, v49
	v_div_fmas_f32 v49, v49, v51, v52
	v_div_fixup_f32 v49, v49, v15, v1
	v_sub_f32_e32 v49, v49, v27
	v_sub_f32_e32 v1, v1, v20
	v_bfe_u32 v50, v49, 16, 1
	v_add_f32_e32 v1, v1, v28
	s_mov_b32 s2, 0x3e000000
	v_add3_u32 v49, v49, v50, s33
	v_fma_f32 v20, v1, s2, -v28
	ds_write_b16_d16_hi v101, v49 offset:1632
	v_bfe_u32 v49, v20, 16, 1
	v_sub_f32_e32 v1, v1, v24
	v_add3_u32 v20, v20, v49, s33
	v_add_f32_e32 v1, v1, v29
	ds_write_b16_d16_hi v101, v20 offset:1904
	v_fma_f32 v20, v1, s2, -v29
	v_sub_f32_e32 v1, v1, v6
	v_bfe_u32 v24, v20, 16, 1
	v_add_f32_e32 v1, v1, v30
	v_add3_u32 v20, v20, v24, s33
	v_fma_f32 v6, v1, s2, -v30
	ds_write_b16_d16_hi v101, v20 offset:2176
	v_bfe_u32 v20, v6, 16, 1
	v_sub_f32_e32 v1, v1, v7
	v_add3_u32 v6, v6, v20, s33
	v_add_f32_e32 v1, v1, v31
	ds_write_b16_d16_hi v101, v6 offset:2448
	v_fma_f32 v6, v1, s2, -v31
	v_bfe_u32 v7, v6, 16, 1
	v_sub_f32_e32 v1, v1, v23
	v_add3_u32 v6, v6, v7, s33
	v_add_f32_e32 v1, v1, v32
	ds_write_b16_d16_hi v101, v6 offset:2720
	v_fma_f32 v6, v1, s2, -v32
	v_bfe_u32 v7, v6, 16, 1
	v_sub_f32_e32 v1, v1, v25
	v_add3_u32 v6, v6, v7, s33
	v_add_f32_e32 v1, v1, v33
	ds_write_b16_d16_hi v101, v6 offset:2992
	v_fma_f32 v6, v1, s2, -v33
	v_bfe_u32 v7, v6, 16, 1
	v_sub_f32_e32 v1, v1, v26
	v_add3_u32 v6, v6, v7, s33
	v_add_f32_e32 v1, v1, v34
	ds_write_b16_d16_hi v101, v6 offset:3264
	v_fma_f32 v6, v1, s2, -v34
	v_bfe_u32 v7, v6, 16, 1
	v_sub_f32_e32 v1, v1, v27
	v_add3_u32 v6, v6, v7, s33
	v_add_f32_e32 v1, v1, v35
	ds_write_b16_d16_hi v101, v6 offset:3536
	v_fma_f32 v6, v1, s2, -v35
	v_bfe_u32 v7, v6, 16, 1
	v_add3_u32 v6, v6, v7, s33
	ds_write_b16_d16_hi v101, v6 offset:3808
	v_add_f32_e32 v6, 0, v19
	v_add_f32_e32 v6, v6, v37
	v_add_f32_e32 v6, v6, v36
	v_add_f32_e32 v6, v6, v42
	v_add_f32_e32 v6, v6, v41
	v_add_f32_e32 v6, v6, v45
	v_lshlrev_b32_e32 v39, 16, v39
	v_add_f32_e32 v6, v6, v4
	v_add_f32_e32 v6, v6, v39
	v_sub_f32_e32 v1, v1, v28
	v_div_scale_f32 v7, s[0:1], v48, v48, v6
	v_add_f32_e32 v1, v1, v21
	v_rcp_f32_e32 v20, v7
	v_fma_f32 v1, v1, s2, -v21
	v_bfe_u32 v21, v1, 16, 1
	v_add3_u32 v1, v1, v21, s33
	ds_write_b16_d16_hi v101, v1 offset:4080
	v_fma_f32 v1, -v7, v20, 1.0
	v_fmac_f32_e32 v20, v1, v20
	v_div_scale_f32 v1, vcc, v6, v48, v6
	v_mul_f32_e32 v21, v1, v20
	v_fma_f32 v23, -v7, v21, v1
	v_fmac_f32_e32 v21, v23, v20
	v_fma_f32 v1, -v7, v21, v1
	v_div_fmas_f32 v1, v1, v20, v21
	v_lshlrev_b32_e32 v47, 16, v60
	v_div_fixup_f32 v1, v1, v48, v6
	v_sub_f32_e32 v6, v6, v19
	v_add_f32_e32 v6, v6, v47
	v_div_scale_f32 v7, s[0:1], v9, v9, v6
	v_rcp_f32_e32 v19, v7
	v_sub_f32_e32 v1, v1, v39
	v_bfe_u32 v20, v1, 16, 1
	v_add3_u32 v1, v1, v20, s33
	ds_write_b16_d16_hi v101, v1 offset:128
	v_fma_f32 v1, -v7, v19, 1.0
	v_fmac_f32_e32 v19, v1, v19
	v_div_scale_f32 v1, vcc, v6, v9, v6
	v_mul_f32_e32 v20, v1, v19
	v_fma_f32 v21, -v7, v20, v1
	v_fmac_f32_e32 v20, v21, v19
	v_fma_f32 v1, -v7, v20, v1
	v_div_fmas_f32 v1, v1, v19, v20
	v_lshlrev_b32_e32 v46, 16, v59
	v_div_fixup_f32 v1, v1, v9, v6
	v_sub_f32_e32 v6, v6, v37
	v_add_f32_e32 v6, v6, v46
	v_div_scale_f32 v7, s[0:1], v8, v8, v6
	v_rcp_f32_e32 v9, v7
	v_sub_f32_e32 v1, v1, v47
	v_bfe_u32 v19, v1, 16, 1
	v_add3_u32 v1, v1, v19, s33
	ds_write_b16_d16_hi v101, v1 offset:400
	v_fma_f32 v1, -v7, v9, 1.0
	v_fmac_f32_e32 v9, v1, v9
	v_div_scale_f32 v1, vcc, v6, v8, v6
	v_mul_f32_e32 v19, v1, v9
	v_fma_f32 v20, -v7, v19, v1
	v_fmac_f32_e32 v19, v20, v9
	v_fma_f32 v1, -v7, v19, v1
	v_div_fmas_f32 v1, v1, v9, v19
	v_lshlrev_b32_e32 v44, 16, v58
	v_div_fixup_f32 v1, v1, v8, v6
	v_sub_f32_e32 v6, v6, v36
	v_add_f32_e32 v6, v6, v44
	v_div_scale_f32 v7, s[0:1], v12, v12, v6
	v_rcp_f32_e32 v8, v7
	v_sub_f32_e32 v1, v1, v46
	v_bfe_u32 v9, v1, 16, 1
	v_add3_u32 v1, v1, v9, s33
	ds_write_b16_d16_hi v101, v1 offset:672
	v_fma_f32 v1, -v7, v8, 1.0
	v_fmac_f32_e32 v8, v1, v8
	v_div_scale_f32 v1, vcc, v6, v12, v6
	v_mul_f32_e32 v9, v1, v8
	v_fma_f32 v19, -v7, v9, v1
	v_fmac_f32_e32 v9, v19, v8
	v_fma_f32 v1, -v7, v9, v1
	v_div_fmas_f32 v1, v1, v8, v9
	v_lshlrev_b32_e32 v43, 16, v57
	v_div_fixup_f32 v1, v1, v12, v6
	v_sub_f32_e32 v6, v6, v42
	v_add_f32_e32 v6, v6, v43
	v_div_scale_f32 v7, s[0:1], v11, v11, v6
	v_rcp_f32_e32 v8, v7
	v_sub_f32_e32 v1, v1, v44
	v_bfe_u32 v9, v1, 16, 1
	v_add3_u32 v1, v1, v9, s33
	ds_write_b16_d16_hi v101, v1 offset:944
	v_fma_f32 v1, -v7, v8, 1.0
	v_fmac_f32_e32 v8, v1, v8
	v_div_scale_f32 v1, vcc, v6, v11, v6
	v_mul_f32_e32 v9, v1, v8
	v_fma_f32 v12, -v7, v9, v1
	v_fmac_f32_e32 v9, v12, v8
	v_fma_f32 v1, -v7, v9, v1
	v_div_fmas_f32 v1, v1, v8, v9
	v_lshlrev_b32_e32 v40, 16, v56
	v_div_fixup_f32 v1, v1, v11, v6
	v_sub_f32_e32 v6, v6, v41
	v_add_f32_e32 v6, v6, v40
	v_div_scale_f32 v7, s[0:1], v16, v16, v6
	v_rcp_f32_e32 v8, v7
	v_sub_f32_e32 v1, v1, v43
	v_bfe_u32 v9, v1, 16, 1
	v_add3_u32 v1, v1, v9, s33
	ds_write_b16_d16_hi v101, v1 offset:1216
	v_fma_f32 v1, -v7, v8, 1.0
	v_fmac_f32_e32 v8, v1, v8
	v_div_scale_f32 v1, vcc, v6, v16, v6
	v_mul_f32_e32 v9, v1, v8
	v_fma_f32 v11, -v7, v9, v1
	v_fmac_f32_e32 v9, v11, v8
	v_fma_f32 v1, -v7, v9, v1
	v_div_fmas_f32 v1, v1, v8, v9
	v_lshlrev_b32_e32 v38, 16, v55
	v_div_fixup_f32 v1, v1, v16, v6
	v_sub_f32_e32 v6, v6, v45
	v_add_f32_e32 v6, v6, v38
	v_div_scale_f32 v7, s[0:1], v15, v15, v6
	v_rcp_f32_e32 v8, v7
	v_sub_f32_e32 v1, v1, v40
	v_bfe_u32 v9, v1, 16, 1
	v_add3_u32 v1, v1, v9, s33
	ds_write_b16_d16_hi v101, v1 offset:1488
	v_fma_f32 v1, -v7, v8, 1.0
	v_fmac_f32_e32 v8, v1, v8
	v_div_scale_f32 v1, vcc, v6, v15, v6
	v_mul_f32_e32 v9, v1, v8
	v_fma_f32 v11, -v7, v9, v1
	v_fmac_f32_e32 v9, v11, v8
	v_fma_f32 v1, -v7, v9, v1
	v_div_fmas_f32 v1, v1, v8, v9
	v_div_fixup_f32 v1, v1, v15, v6
	v_sub_f32_e32 v1, v1, v38
	v_bfe_u32 v7, v1, 16, 1
	v_add3_u32 v1, v1, v7, s33
	v_lshlrev_b32_e32 v22, 16, v54
	ds_write_b16_d16_hi v101, v1 offset:1760
	v_sub_f32_e32 v1, v6, v4
	v_add_f32_e32 v1, v1, v22
	v_fma_f32 v4, v1, s2, -v22
	v_bfe_u32 v6, v4, 16, 1
	v_sub_f32_e32 v1, v1, v39
	v_add3_u32 v4, v4, v6, s33
	v_add_f32_e32 v1, v1, v18
	ds_write_b16_d16_hi v101, v4 offset:2032
	v_fma_f32 v4, v1, s2, -v18
	v_bfe_u32 v6, v4, 16, 1
	v_sub_f32_e32 v1, v1, v47
	v_add3_u32 v4, v4, v6, s33
	v_add_f32_e32 v1, v1, v17
	ds_write_b16_d16_hi v101, v4 offset:2304
	v_fma_f32 v4, v1, s2, -v17
	v_bfe_u32 v6, v4, 16, 1
	v_sub_f32_e32 v1, v1, v46
	v_add3_u32 v4, v4, v6, s33
	v_add_f32_e32 v1, v1, v14
	ds_write_b16_d16_hi v101, v4 offset:2576
	v_fma_f32 v4, v1, s2, -v14
	v_bfe_u32 v6, v4, 16, 1
	v_sub_f32_e32 v1, v1, v44
	v_add3_u32 v4, v4, v6, s33
	v_add_f32_e32 v1, v1, v13
	ds_write_b16_d16_hi v101, v4 offset:2848
	v_fma_f32 v4, v1, s2, -v13
	v_bfe_u32 v6, v4, 16, 1
	v_sub_f32_e32 v1, v1, v43
	v_add3_u32 v4, v4, v6, s33
	v_add_f32_e32 v1, v1, v10
	ds_write_b16_d16_hi v101, v4 offset:3120
	v_fma_f32 v4, v1, s2, -v10
	v_bfe_u32 v6, v4, 16, 1
	v_sub_f32_e32 v1, v1, v40
	v_add3_u32 v4, v4, v6, s33
	v_add_f32_e32 v1, v1, v5
	ds_write_b16_d16_hi v101, v4 offset:3392
	v_fma_f32 v4, v1, s2, -v5
	v_sub_f32_e32 v1, v1, v38
	v_add_f32_e32 v1, v1, v3
	v_fma_f32 v3, v1, s2, -v3
	v_sub_f32_e32 v1, v1, v22
	v_bfe_u32 v5, v4, 16, 1
	v_add_f32_e32 v1, v1, v2
	v_add3_u32 v4, v4, v5, s33
	v_fma_f32 v1, v1, s2, -v2
	ds_write_b16_d16_hi v101, v4 offset:3664
	v_bfe_u32 v4, v3, 16, 1
	v_bfe_u32 v2, v1, 16, 1
	v_add3_u32 v3, v3, v4, s33
	v_add3_u32 v1, v1, v2, s33
	ds_write_b16_d16_hi v101, v3 offset:3936
	ds_write_b16_d16_hi v101, v1 offset:4208
	ds_read_b128 v[6:9], v105
	ds_read_b128 v[10:13], v105 offset:64
	ds_read_b128 v[14:17], v105 offset:128
	ds_read_b128 v[2:5], v105 offset:192
	v_readlane_b32 s74, v251, 54
	v_readlane_b32 s70, v251, 58
	v_readlane_b32 s68, v251, 60
	v_readlane_b32 s34, v250, 0
	v_readlane_b32 s73, v251, 53
	v_readlane_b32 s75, v251, 55
	v_readlane_b32 s71, v251, 59
	v_readlane_b32 s69, v251, 61
	v_readlane_b32 s35, v250, 1
	s_mov_b64 s[36:37], 0x8000
	s_mov_b64 s[40:41], 0xc400
	global_load_dwordx4 v[18:21], v[78:79], off
	global_load_dwordx4 v[22:25], v[78:79], off offset:64
	global_load_dwordx4 v[26:29], v[78:79], off offset:128
	global_load_dwordx4 v[30:33], v[78:79], off offset:192
	v_add_co_u32_e32 v78, vcc, 0x1000, v78
	s_nop 1
	v_addc_co_u32_e32 v79, vcc, 0, v79, vcc
	global_load_dwordx4 v[34:37], v[78:79], off
	global_load_dwordx4 v[38:41], v[78:79], off offset:64
	global_load_dwordx4 v[42:45], v[78:79], off offset:128
	global_load_dwordx4 v[46:49], v[78:79], off offset:192
	v_add_co_u32_e32 v78, vcc, 0x1000, v78
	s_nop 1
	v_addc_co_u32_e32 v79, vcc, 0, v79, vcc
	global_load_dwordx4 v[50:53], v[78:79], off
	global_load_dwordx4 v[54:57], v[78:79], off offset:64
	global_load_dwordx4 v[58:61], v[78:79], off offset:128
	global_load_dwordx4 v[62:65], v[78:79], off offset:192
	v_add_co_u32_e32 v78, vcc, 0x1000, v78
	s_nop 1
	v_addc_co_u32_e32 v79, vcc, 0, v79, vcc
	global_load_dwordx4 v[66:69], v[78:79], off
	global_load_dwordx4 v[70:73], v[78:79], off offset:64
	global_load_dwordx4 v[74:77], v[78:79], off offset:128
	global_load_dwordx4 v[240:243], v[78:79], off offset:192
	v_add_co_u32_e32 v78, vcc, 0x1000, v78
	s_nop 1
	v_addc_co_u32_e32 v79, vcc, 0, v79, vcc
	global_load_dwordx4 v[174:177], v[78:79], off
	global_load_dwordx4 v[178:181], v[78:79], off offset:64
	global_load_dwordx4 v[182:185], v[78:79], off offset:128
	global_load_dwordx4 v[186:189], v[78:79], off offset:192
	v_add_co_u32_e32 v78, vcc, 0x1000, v78
	s_nop 1
	v_addc_co_u32_e32 v79, vcc, 0, v79, vcc
	global_load_dwordx4 v[190:193], v[78:79], off
	global_load_dwordx4 v[194:197], v[78:79], off offset:64
	global_load_dwordx4 v[198:201], v[78:79], off offset:128
	global_load_dwordx4 v[202:205], v[78:79], off offset:192
	v_add_co_u32_e32 v78, vcc, 0x1000, v78
	s_nop 1
	v_addc_co_u32_e32 v79, vcc, 0, v79, vcc
	global_load_dwordx4 v[206:209], v[78:79], off
	global_load_dwordx4 v[210:213], v[78:79], off offset:64
	global_load_dwordx4 v[214:217], v[78:79], off offset:128
	global_load_dwordx4 v[218:221], v[78:79], off offset:192
	v_add_co_u32_e32 v78, vcc, 0x1000, v78
	s_nop 1
	v_addc_co_u32_e32 v79, vcc, 0, v79, vcc
	global_load_dwordx4 v[222:225], v[78:79], off
	global_load_dwordx4 v[226:229], v[78:79], off offset:64
	global_load_dwordx4 v[230:233], v[78:79], off offset:128
	global_load_dwordx4 v[234:237], v[78:79], off offset:192
	v_lshlrev_b64 v[244:245], 11, v[90:91]
	v_lshl_add_u64 v[244:245], v[120:121], 0, v[244:245]
	s_waitcnt lgkmcnt(0)
	s_waitcnt vmcnt(28)
	v_mfma_f32_16x16x32_bf16 v[18:21], v[18:21], v[6:9], 0
	v_mfma_f32_16x16x32_bf16 v[18:21], v[22:25], v[10:13], v[18:21]
	v_mfma_f32_16x16x32_bf16 v[18:21], v[26:29], v[14:17], v[18:21]
	v_mfma_f32_16x16x32_bf16 v[18:21], v[30:33], v[2:5], v[18:21]
	s_waitcnt vmcnt(24)
	v_mfma_f32_16x16x32_bf16 v[34:37], v[34:37], v[6:9], 0
	v_mfma_f32_16x16x32_bf16 v[34:37], v[38:41], v[10:13], v[34:37]
	v_mfma_f32_16x16x32_bf16 v[34:37], v[42:45], v[14:17], v[34:37]
	v_mfma_f32_16x16x32_bf16 v[34:37], v[46:49], v[2:5], v[34:37]
	global_load_dwordx4 v[22:25], v[126:127], off offset:1024
	global_load_dwordx4 v[26:29], v[126:127], off offset:1088
	global_load_dwordx4 v[30:33], v[126:127], off offset:1152
	s_waitcnt vmcnt(23)
	v_mfma_f32_16x16x32_bf16 v[50:53], v[50:53], v[6:9], 0
	v_mfma_f32_16x16x32_bf16 v[50:53], v[54:57], v[10:13], v[50:53]
	v_mfma_f32_16x16x32_bf16 v[50:53], v[58:61], v[14:17], v[50:53]
	v_mfma_f32_16x16x32_bf16 v[50:53], v[62:65], v[2:5], v[50:53]
	global_load_dwordx4 v[38:41], v[126:127], off offset:1216
	global_load_dwordx4 v[42:45], v[126:127], off offset:1280
	global_load_dwordx4 v[46:49], v[126:127], off offset:1344
	s_waitcnt vmcnt(22)
	v_mfma_f32_16x16x32_bf16 v[66:69], v[66:69], v[6:9], 0
	v_mfma_f32_16x16x32_bf16 v[66:69], v[70:73], v[10:13], v[66:69]
	v_mfma_f32_16x16x32_bf16 v[66:69], v[74:77], v[14:17], v[66:69]
	v_mfma_f32_16x16x32_bf16 v[66:69], v[240:243], v[2:5], v[66:69]
	global_load_dwordx4 v[54:57], v[126:127], off offset:1408
	global_load_dwordx4 v[58:61], v[126:127], off offset:1472
	s_waitcnt vmcnt(20)
	v_mfma_f32_16x16x32_bf16 v[174:177], v[174:177], v[6:9], 0
	v_mfma_f32_16x16x32_bf16 v[174:177], v[178:181], v[10:13], v[174:177]
	v_mfma_f32_16x16x32_bf16 v[174:177], v[182:185], v[14:17], v[174:177]
	v_mfma_f32_16x16x32_bf16 v[174:177], v[186:189], v[2:5], v[174:177]
	s_waitcnt vmcnt(16)
	v_mfma_f32_16x16x32_bf16 v[190:193], v[190:193], v[6:9], 0
	v_mfma_f32_16x16x32_bf16 v[190:193], v[194:197], v[10:13], v[190:193]
	v_mfma_f32_16x16x32_bf16 v[190:193], v[198:201], v[14:17], v[190:193]
	v_mfma_f32_16x16x32_bf16 v[190:193], v[202:205], v[2:5], v[190:193]
	s_waitcnt vmcnt(12)
	v_mfma_f32_16x16x32_bf16 v[206:209], v[206:209], v[6:9], 0
	v_mfma_f32_16x16x32_bf16 v[206:209], v[210:213], v[10:13], v[206:209]
	v_mfma_f32_16x16x32_bf16 v[206:209], v[214:217], v[14:17], v[206:209]
	v_mfma_f32_16x16x32_bf16 v[206:209], v[218:221], v[2:5], v[206:209]
	s_waitcnt vmcnt(8)
	v_mfma_f32_16x16x32_bf16 v[222:225], v[222:225], v[6:9], 0
	v_mfma_f32_16x16x32_bf16 v[222:225], v[226:229], v[10:13], v[222:225]
	v_mfma_f32_16x16x32_bf16 v[222:225], v[230:233], v[14:17], v[222:225]
	v_mfma_f32_16x16x32_bf16 v[222:225], v[234:237], v[2:5], v[222:225]
	s_nop 7
	s_waitcnt vmcnt(5)
	v_pk_mul_f32 v[18:19], v[18:19], v[22:23]
	v_pk_mul_f32 v[20:21], v[20:21], v[24:25]
	v_cvt_pk_bf16_f32 v18, v18, v19
	v_cvt_pk_bf16_f32 v19, v20, v21
	global_store_dwordx2 v[244:245], v[18:19], off offset:1536
	v_pk_mul_f32 v[34:35], v[34:35], v[26:27]
	v_pk_mul_f32 v[36:37], v[36:37], v[28:29]
	v_cvt_pk_bf16_f32 v34, v34, v35
	v_cvt_pk_bf16_f32 v35, v36, v37
	global_store_dwordx2 v[244:245], v[34:35], off offset:1568
	v_pk_mul_f32 v[50:51], v[50:51], v[30:31]
	v_pk_mul_f32 v[52:53], v[52:53], v[32:33]
	v_cvt_pk_bf16_f32 v50, v50, v51
	v_cvt_pk_bf16_f32 v51, v52, v53
	global_store_dwordx2 v[244:245], v[50:51], off offset:1600
	s_waitcnt vmcnt(2)
	v_pk_mul_f32 v[66:67], v[66:67], v[38:39]
	v_pk_mul_f32 v[68:69], v[68:69], v[40:41]
	v_cvt_pk_bf16_f32 v66, v66, v67
	v_cvt_pk_bf16_f32 v67, v68, v69
	global_store_dwordx2 v[244:245], v[66:67], off offset:1632
	v_pk_mul_f32 v[174:175], v[174:175], v[42:43]
	v_pk_mul_f32 v[176:177], v[176:177], v[44:45]
	v_cvt_pk_bf16_f32 v174, v174, v175
	v_cvt_pk_bf16_f32 v175, v176, v177
	global_store_dwordx2 v[244:245], v[174:175], off offset:1664
	v_pk_mul_f32 v[190:191], v[190:191], v[46:47]
	v_pk_mul_f32 v[192:193], v[192:193], v[48:49]
	v_cvt_pk_bf16_f32 v190, v190, v191
	v_cvt_pk_bf16_f32 v191, v192, v193
	global_store_dwordx2 v[244:245], v[190:191], off offset:1696
	s_waitcnt vmcnt(0)
	v_pk_mul_f32 v[206:207], v[206:207], v[54:55]
	v_pk_mul_f32 v[208:209], v[208:209], v[56:57]
	v_cvt_pk_bf16_f32 v206, v206, v207
	v_cvt_pk_bf16_f32 v207, v208, v209
	global_store_dwordx2 v[244:245], v[206:207], off offset:1728
	v_pk_mul_f32 v[222:223], v[222:223], v[58:59]
	v_pk_mul_f32 v[224:225], v[224:225], v[60:61]
	v_cvt_pk_bf16_f32 v222, v222, v223
	v_cvt_pk_bf16_f32 v223, v224, v225
	global_store_dwordx2 v[244:245], v[222:223], off offset:1760

.LBB0_799:
	v_lshl_add_u64 v[22:23], v[128:129], 0, s[2:3]
	v_lshl_add_u64 v[24:25], v[128:129], 0, s[10:11]
	v_lshl_add_u64 v[26:27], v[128:129], 0, s[26:27]
	v_lshl_add_u64 v[28:29], v[128:129], 0, s[28:29]
	v_lshl_add_u64 v[30:31], v[128:129], 0, s[30:31]
	v_lshl_add_u64 v[32:33], v[128:129], 0, s[34:35]
	v_lshl_add_u64 v[34:35], v[128:129], 0, s[38:39]
	v_lshl_add_u64 v[36:37], v[128:129], 0, s[40:41]
	v_lshl_add_u64 v[38:39], v[128:129], 0, s[42:43]
	v_lshl_add_u64 v[40:41], v[128:129], 0, s[46:47]
	v_lshl_add_u64 v[42:43], v[128:129], 0, s[48:49]
	v_lshl_add_u64 v[44:45], v[128:129], 0, s[50:51]
	v_lshl_add_u64 v[46:47], v[128:129], 0, s[56:57]
	v_lshl_add_u64 v[48:49], v[128:129], 0, s[58:59]
	v_lshl_add_u64 v[50:51], v[128:129], 0, s[66:67]
	v_lshl_add_u64 v[52:53], v[128:129], 0, s[60:61]
	global_load_ushort v3, v[50:51], off
	s_nop 0
	global_load_ushort v50, v[52:53], off
	s_nop 0
	global_load_ushort v48, v[48:49], off
	s_nop 0
	global_load_ushort v46, v[46:47], off
	s_nop 0
	global_load_ushort v44, v[44:45], off
	s_nop 0
	global_load_ushort v42, v[42:43], off
	s_nop 0
	global_load_ushort v40, v[40:41], off
	s_nop 0
	global_load_ushort v38, v[38:39], off
	s_nop 0
	global_load_ushort v36, v[36:37], off
	s_nop 0
	global_load_ushort v34, v[34:35], off
	s_nop 0
	global_load_ushort v32, v[32:33], off
	s_nop 0
	global_load_ushort v30, v[30:31], off
	s_nop 0
	global_load_ushort v28, v[28:29], off
	s_nop 0
	global_load_ushort v26, v[26:27], off
	s_nop 0
	global_load_ushort v24, v[24:25], off
	s_nop 0
	global_load_ushort v22, v[22:23], off
	s_waitcnt vmcnt(0)
	v_lshlrev_b32_e32 v1, 16, v1
	s_or_b32 s0, s12, s21
	v_cndmask_b32_e64 v1, v1, v5, s[22:23]
	s_cmp_eq_u32 s0, 0
	v_lshlrev_b32_e32 v6, 16, v6
	v_add_f32_e32 v5, 0, v1
	s_cselect_b32 s0, 1, 2
	v_add_f32_e32 v5, v5, v6
	v_cvt_f32_ubyte0_e32 v23, s0
	v_div_scale_f32 v25, s[0:1], v23, v23, v5
	v_rcp_f32_e32 v27, v25
	v_lshlrev_b32_e32 v2, 16, v2
	v_cndmask_b32_e64 v2, v2, v4, s[22:23]
	v_div_scale_f32 v4, vcc, v5, v23, v5
	v_fma_f32 v29, -v25, v27, 1.0
	v_fmac_f32_e32 v27, v29, v27
	v_mul_f32_e32 v29, v4, v27
	v_fma_f32 v41, -v25, v29, v4
	v_fmac_f32_e32 v29, v41, v27
	v_fma_f32 v4, -v25, v29, v4
	v_div_fmas_f32 v4, v4, v27, v29
	v_div_fixup_f32 v4, v4, v23, v5
	v_sub_f32_e32 v4, v4, v6
	v_lshlrev_b32_e32 v7, 16, v7
	v_bfe_u32 v25, v4, 16, 1
	v_sub_f32_e32 v1, v5, v1
	v_add3_u32 v4, v4, v25, s33
	v_add_f32_e32 v1, v1, v7
	ds_write_b16_d16_hi v101, v4
	v_fma_f32 v4, v1, 0.5, -v7
	v_lshlrev_b32_e32 v8, 16, v8
	v_bfe_u32 v5, v4, 16, 1
	v_sub_f32_e32 v1, v1, v6
	v_add3_u32 v4, v4, v5, s33
	v_add_f32_e32 v1, v1, v8
	ds_write_b16_d16_hi v101, v4 offset:272
	v_fma_f32 v4, v1, 0.5, -v8
	v_lshlrev_b32_e32 v9, 16, v9
	v_bfe_u32 v5, v4, 16, 1
	v_sub_f32_e32 v1, v1, v7
	v_add3_u32 v4, v4, v5, s33
	v_add_f32_e32 v1, v1, v9
	ds_write_b16_d16_hi v101, v4 offset:544
	v_fma_f32 v4, v1, 0.5, -v9
	v_lshlrev_b32_e32 v10, 16, v10
	v_bfe_u32 v5, v4, 16, 1
	v_sub_f32_e32 v1, v1, v8
	v_add3_u32 v4, v4, v5, s33
	v_add_f32_e32 v1, v1, v10
	ds_write_b16_d16_hi v101, v4 offset:816
	v_fma_f32 v4, v1, 0.5, -v10
	v_lshlrev_b32_e32 v11, 16, v11
	v_bfe_u32 v5, v4, 16, 1
	v_sub_f32_e32 v1, v1, v9
	v_add3_u32 v4, v4, v5, s33
	v_add_f32_e32 v1, v1, v11
	ds_write_b16_d16_hi v101, v4 offset:1088
	v_fma_f32 v4, v1, 0.5, -v11
	v_lshlrev_b32_e32 v12, 16, v12
	v_bfe_u32 v5, v4, 16, 1
	v_sub_f32_e32 v1, v1, v10
	v_add3_u32 v4, v4, v5, s33
	v_add_f32_e32 v1, v1, v12
	ds_write_b16_d16_hi v101, v4 offset:1360
	v_fma_f32 v4, v1, 0.5, -v12
	v_lshlrev_b32_e32 v13, 16, v13
	v_bfe_u32 v5, v4, 16, 1
	v_sub_f32_e32 v1, v1, v11
	v_add3_u32 v4, v4, v5, s33
	v_add_f32_e32 v1, v1, v13
	ds_write_b16_d16_hi v101, v4 offset:1632
	v_fma_f32 v4, v1, 0.5, -v13
	v_lshlrev_b32_e32 v14, 16, v14
	v_bfe_u32 v5, v4, 16, 1
	v_sub_f32_e32 v1, v1, v12
	v_add3_u32 v4, v4, v5, s33
	v_add_f32_e32 v1, v1, v14
	ds_write_b16_d16_hi v101, v4 offset:1904
	v_fma_f32 v4, v1, 0.5, -v14
	v_lshlrev_b32_e32 v15, 16, v15
	v_bfe_u32 v5, v4, 16, 1
	v_sub_f32_e32 v1, v1, v13
	v_add3_u32 v4, v4, v5, s33
	v_add_f32_e32 v1, v1, v15
	ds_write_b16_d16_hi v101, v4 offset:2176
	v_fma_f32 v4, v1, 0.5, -v15
	v_lshlrev_b32_e32 v16, 16, v16
	v_bfe_u32 v5, v4, 16, 1
	v_sub_f32_e32 v1, v1, v14
	v_add3_u32 v4, v4, v5, s33
	v_add_f32_e32 v1, v1, v16
	ds_write_b16_d16_hi v101, v4 offset:2448
	v_fma_f32 v4, v1, 0.5, -v16
	v_lshlrev_b32_e32 v17, 16, v17
	v_bfe_u32 v5, v4, 16, 1
	v_sub_f32_e32 v1, v1, v15
	v_add3_u32 v4, v4, v5, s33
	v_add_f32_e32 v1, v1, v17
	ds_write_b16_d16_hi v101, v4 offset:2720
	v_fma_f32 v4, v1, 0.5, -v17
	v_lshlrev_b32_e32 v18, 16, v18
	v_bfe_u32 v5, v4, 16, 1
	v_sub_f32_e32 v1, v1, v16
	v_add3_u32 v4, v4, v5, s33
	v_add_f32_e32 v1, v1, v18
	ds_write_b16_d16_hi v101, v4 offset:2992
	v_fma_f32 v4, v1, 0.5, -v18
	v_lshlrev_b32_e32 v19, 16, v19
	v_bfe_u32 v5, v4, 16, 1
	v_sub_f32_e32 v1, v1, v17
	v_add3_u32 v4, v4, v5, s33
	v_add_f32_e32 v1, v1, v19
	ds_write_b16_d16_hi v101, v4 offset:3264
	v_fma_f32 v4, v1, 0.5, -v19
	v_lshlrev_b32_e32 v20, 16, v20
	v_bfe_u32 v5, v4, 16, 1
	v_sub_f32_e32 v1, v1, v18
	v_add3_u32 v4, v4, v5, s33
	v_add_f32_e32 v1, v1, v20
	ds_write_b16_d16_hi v101, v4 offset:3536
	v_fma_f32 v4, v1, 0.5, -v20
	v_bfe_u32 v5, v4, 16, 1
	v_add3_u32 v4, v4, v5, s33
	v_lshlrev_b32_e32 v22, 16, v22
	ds_write_b16_d16_hi v101, v4 offset:3808
	v_add_f32_e32 v4, 0, v2
	v_add_f32_e32 v4, v4, v22
	v_lshlrev_b32_e32 v21, 16, v21
	v_sub_f32_e32 v1, v1, v19
	v_div_scale_f32 v5, s[0:1], v23, v23, v4
	v_add_f32_e32 v1, v1, v21
	v_rcp_f32_e32 v6, v5
	v_fma_f32 v1, v1, 0.5, -v21
	v_bfe_u32 v7, v1, 16, 1
	v_add3_u32 v1, v1, v7, s33
	ds_write_b16_d16_hi v101, v1 offset:4080
	v_fma_f32 v1, -v5, v6, 1.0
	v_fmac_f32_e32 v6, v1, v6
	v_div_scale_f32 v1, vcc, v4, v23, v4
	v_mul_f32_e32 v7, v1, v6
	v_fma_f32 v8, -v5, v7, v1
	v_fmac_f32_e32 v7, v8, v6
	v_fma_f32 v1, -v5, v7, v1
	v_div_fmas_f32 v1, v1, v6, v7
	v_div_fixup_f32 v1, v1, v23, v4
	v_sub_f32_e32 v1, v1, v22
	v_bfe_u32 v5, v1, 16, 1
	v_add3_u32 v1, v1, v5, s33
	v_lshlrev_b32_e32 v24, 16, v24
	ds_write_b16_d16_hi v101, v1 offset:128
	v_sub_f32_e32 v1, v4, v2
	v_add_f32_e32 v1, v1, v24
	v_fma_f32 v2, v1, 0.5, -v24
	v_lshlrev_b32_e32 v26, 16, v26
	v_bfe_u32 v4, v2, 16, 1
	v_sub_f32_e32 v1, v1, v22
	v_add3_u32 v2, v2, v4, s33
	v_add_f32_e32 v1, v1, v26
	ds_write_b16_d16_hi v101, v2 offset:400
	v_fma_f32 v2, v1, 0.5, -v26
	v_lshlrev_b32_e32 v28, 16, v28
	v_bfe_u32 v4, v2, 16, 1
	v_sub_f32_e32 v1, v1, v24
	v_add3_u32 v2, v2, v4, s33
	v_add_f32_e32 v1, v1, v28
	ds_write_b16_d16_hi v101, v2 offset:672
	v_fma_f32 v2, v1, 0.5, -v28
	v_lshlrev_b32_e32 v30, 16, v30
	v_bfe_u32 v4, v2, 16, 1
	v_sub_f32_e32 v1, v1, v26
	v_add3_u32 v2, v2, v4, s33
	v_add_f32_e32 v1, v1, v30
	ds_write_b16_d16_hi v101, v2 offset:944
	v_fma_f32 v2, v1, 0.5, -v30
	v_lshlrev_b32_e32 v32, 16, v32
	v_bfe_u32 v4, v2, 16, 1
	v_sub_f32_e32 v1, v1, v28
	v_add3_u32 v2, v2, v4, s33
	v_add_f32_e32 v1, v1, v32
	ds_write_b16_d16_hi v101, v2 offset:1216
	v_fma_f32 v2, v1, 0.5, -v32
	v_lshlrev_b32_e32 v34, 16, v34
	v_bfe_u32 v4, v2, 16, 1
	v_sub_f32_e32 v1, v1, v30
	v_add3_u32 v2, v2, v4, s33
	v_add_f32_e32 v1, v1, v34
	ds_write_b16_d16_hi v101, v2 offset:1488
	v_fma_f32 v2, v1, 0.5, -v34
	v_lshlrev_b32_e32 v36, 16, v36
	v_bfe_u32 v4, v2, 16, 1
	v_sub_f32_e32 v1, v1, v32
	v_add3_u32 v2, v2, v4, s33
	v_add_f32_e32 v1, v1, v36
	ds_write_b16_d16_hi v101, v2 offset:1760
	v_fma_f32 v2, v1, 0.5, -v36
	v_lshlrev_b32_e32 v38, 16, v38
	v_bfe_u32 v4, v2, 16, 1
	v_sub_f32_e32 v1, v1, v34
	v_add3_u32 v2, v2, v4, s33
	v_add_f32_e32 v1, v1, v38
	ds_write_b16_d16_hi v101, v2 offset:2032
	v_fma_f32 v2, v1, 0.5, -v38
	v_lshlrev_b32_e32 v40, 16, v40
	v_bfe_u32 v4, v2, 16, 1
	v_sub_f32_e32 v1, v1, v36
	v_add3_u32 v2, v2, v4, s33
	v_add_f32_e32 v1, v1, v40
	ds_write_b16_d16_hi v101, v2 offset:2304
	v_fma_f32 v2, v1, 0.5, -v40
	v_lshlrev_b32_e32 v39, 16, v42
	v_bfe_u32 v4, v2, 16, 1
	v_sub_f32_e32 v1, v1, v38
	v_add3_u32 v2, v2, v4, s33
	v_add_f32_e32 v1, v1, v39
	ds_write_b16_d16_hi v101, v2 offset:2576
	v_fma_f32 v2, v1, 0.5, -v39
	v_lshlrev_b32_e32 v37, 16, v44
	v_bfe_u32 v4, v2, 16, 1
	v_sub_f32_e32 v1, v1, v40
	v_add3_u32 v2, v2, v4, s33
	v_add_f32_e32 v1, v1, v37
	ds_write_b16_d16_hi v101, v2 offset:2848
	v_fma_f32 v2, v1, 0.5, -v37
	v_lshlrev_b32_e32 v35, 16, v46
	v_bfe_u32 v4, v2, 16, 1
	v_sub_f32_e32 v1, v1, v39
	v_add3_u32 v2, v2, v4, s33
	v_add_f32_e32 v1, v1, v35
	ds_write_b16_d16_hi v101, v2 offset:3120
	v_fma_f32 v2, v1, 0.5, -v35
	v_lshlrev_b32_e32 v33, 16, v48
	v_bfe_u32 v4, v2, 16, 1
	v_sub_f32_e32 v1, v1, v37
	v_add3_u32 v2, v2, v4, s33
	v_add_f32_e32 v1, v1, v33
	ds_write_b16_d16_hi v101, v2 offset:3392
	v_fma_f32 v2, v1, 0.5, -v33
	v_lshlrev_b32_e32 v31, 16, v50
	v_bfe_u32 v4, v2, 16, 1
	v_sub_f32_e32 v1, v1, v35
	v_add3_u32 v2, v2, v4, s33
	v_add_f32_e32 v1, v1, v31
	v_lshlrev_b32_e32 v3, 16, v3
	ds_write_b16_d16_hi v101, v2 offset:3664
	v_fma_f32 v2, v1, 0.5, -v31
	v_sub_f32_e32 v1, v1, v33
	v_bfe_u32 v4, v2, 16, 1
	v_add_f32_e32 v1, v1, v3
	v_add3_u32 v2, v2, v4, s33
	v_fma_f32 v1, v1, 0.5, -v3
	ds_write_b16_d16_hi v101, v2 offset:3936
	v_bfe_u32 v2, v1, 16, 1
	v_add3_u32 v1, v1, v2, s33
	ds_write_b16_d16_hi v101, v1 offset:4208
	v_mov_b64_e32 v[78:79], v[112:113]
	ds_read_b128 v[6:9], v105
	ds_read_b128 v[10:13], v105 offset:64
	ds_read_b128 v[14:17], v105 offset:128
	ds_read_b128 v[2:5], v105 offset:192
	v_or_b32_e32 v90, s19, v94
	v_readlane_b32 s30, v251, 62
	v_readlane_b32 s34, v250, 0
	s_mov_b64 s[0:1], 0
	v_readlane_b32 s31, v251, 63
	v_readlane_b32 s35, v250, 1
	s_mov_b64 s[36:37], 0x8000
	s_mov_b64 s[38:39], 0x8080
	s_mov_b64 s[40:41], 0xc400
	global_load_dwordx4 v[18:21], v[78:79], off
	global_load_dwordx4 v[22:25], v[78:79], off offset:64
	global_load_dwordx4 v[26:29], v[78:79], off offset:128
	global_load_dwordx4 v[30:33], v[78:79], off offset:192
	v_add_co_u32_e32 v78, vcc, 0x1000, v78
	s_nop 1
	v_addc_co_u32_e32 v79, vcc, 0, v79, vcc
	global_load_dwordx4 v[34:37], v[78:79], off
	global_load_dwordx4 v[38:41], v[78:79], off offset:64
	global_load_dwordx4 v[42:45], v[78:79], off offset:128
	global_load_dwordx4 v[46:49], v[78:79], off offset:192
	v_add_co_u32_e32 v78, vcc, 0x1000, v78
	s_nop 1
	v_addc_co_u32_e32 v79, vcc, 0, v79, vcc
	global_load_dwordx4 v[50:53], v[78:79], off
	global_load_dwordx4 v[54:57], v[78:79], off offset:64
	global_load_dwordx4 v[58:61], v[78:79], off offset:128
	global_load_dwordx4 v[62:65], v[78:79], off offset:192
	v_add_co_u32_e32 v78, vcc, 0x1000, v78
	s_nop 1
	v_addc_co_u32_e32 v79, vcc, 0, v79, vcc
	global_load_dwordx4 v[66:69], v[78:79], off
	global_load_dwordx4 v[70:73], v[78:79], off offset:64
	global_load_dwordx4 v[74:77], v[78:79], off offset:128
	global_load_dwordx4 v[240:243], v[78:79], off offset:192
	v_add_co_u32_e32 v78, vcc, 0x1000, v78
	s_nop 1
	v_addc_co_u32_e32 v79, vcc, 0, v79, vcc
	global_load_dwordx4 v[174:177], v[78:79], off
	global_load_dwordx4 v[178:181], v[78:79], off offset:64
	global_load_dwordx4 v[182:185], v[78:79], off offset:128
	global_load_dwordx4 v[186:189], v[78:79], off offset:192
	v_add_co_u32_e32 v78, vcc, 0x1000, v78
	s_nop 1
	v_addc_co_u32_e32 v79, vcc, 0, v79, vcc
	global_load_dwordx4 v[190:193], v[78:79], off
	global_load_dwordx4 v[194:197], v[78:79], off offset:64
	global_load_dwordx4 v[198:201], v[78:79], off offset:128
	global_load_dwordx4 v[202:205], v[78:79], off offset:192
	v_add_co_u32_e32 v78, vcc, 0x1000, v78
	s_nop 1
	v_addc_co_u32_e32 v79, vcc, 0, v79, vcc
	global_load_dwordx4 v[206:209], v[78:79], off
	global_load_dwordx4 v[210:213], v[78:79], off offset:64
	global_load_dwordx4 v[214:217], v[78:79], off offset:128
	global_load_dwordx4 v[218:221], v[78:79], off offset:192
	v_add_co_u32_e32 v78, vcc, 0x1000, v78
	s_nop 1
	v_addc_co_u32_e32 v79, vcc, 0, v79, vcc
	global_load_dwordx4 v[222:225], v[78:79], off
	global_load_dwordx4 v[226:229], v[78:79], off offset:64
	global_load_dwordx4 v[230:233], v[78:79], off offset:128
	global_load_dwordx4 v[234:237], v[78:79], off offset:192
	v_lshlrev_b64 v[244:245], 11, v[90:91]
	v_lshl_add_u64 v[244:245], v[120:121], 0, v[244:245]
	s_waitcnt lgkmcnt(0)
	s_waitcnt vmcnt(28)
	v_mfma_f32_16x16x32_bf16 v[18:21], v[18:21], v[6:9], 0
	v_mfma_f32_16x16x32_bf16 v[18:21], v[22:25], v[10:13], v[18:21]
	v_mfma_f32_16x16x32_bf16 v[18:21], v[26:29], v[14:17], v[18:21]
	v_mfma_f32_16x16x32_bf16 v[18:21], v[30:33], v[2:5], v[18:21]
	s_waitcnt vmcnt(24)
	v_mfma_f32_16x16x32_bf16 v[34:37], v[34:37], v[6:9], 0
	v_mfma_f32_16x16x32_bf16 v[34:37], v[38:41], v[10:13], v[34:37]
	v_mfma_f32_16x16x32_bf16 v[34:37], v[42:45], v[14:17], v[34:37]
	v_mfma_f32_16x16x32_bf16 v[34:37], v[46:49], v[2:5], v[34:37]
	global_load_dwordx4 v[22:25], v[126:127], off
	global_load_dwordx4 v[26:29], v[126:127], off offset:64
	global_load_dwordx4 v[30:33], v[126:127], off offset:128
	s_waitcnt vmcnt(23)
	v_mfma_f32_16x16x32_bf16 v[50:53], v[50:53], v[6:9], 0
	v_mfma_f32_16x16x32_bf16 v[50:53], v[54:57], v[10:13], v[50:53]
	v_mfma_f32_16x16x32_bf16 v[50:53], v[58:61], v[14:17], v[50:53]
	v_mfma_f32_16x16x32_bf16 v[50:53], v[62:65], v[2:5], v[50:53]
	global_load_dwordx4 v[38:41], v[126:127], off offset:192
	global_load_dwordx4 v[42:45], v[126:127], off offset:256
	global_load_dwordx4 v[46:49], v[126:127], off offset:320
	s_waitcnt vmcnt(22)
	v_mfma_f32_16x16x32_bf16 v[66:69], v[66:69], v[6:9], 0
	v_mfma_f32_16x16x32_bf16 v[66:69], v[70:73], v[10:13], v[66:69]
	v_mfma_f32_16x16x32_bf16 v[66:69], v[74:77], v[14:17], v[66:69]
	v_mfma_f32_16x16x32_bf16 v[66:69], v[240:243], v[2:5], v[66:69]
	global_load_dwordx4 v[54:57], v[126:127], off offset:384
	global_load_dwordx4 v[58:61], v[126:127], off offset:448
	s_waitcnt vmcnt(20)
	v_mfma_f32_16x16x32_bf16 v[174:177], v[174:177], v[6:9], 0
	v_mfma_f32_16x16x32_bf16 v[174:177], v[178:181], v[10:13], v[174:177]
	v_mfma_f32_16x16x32_bf16 v[174:177], v[182:185], v[14:17], v[174:177]
	v_mfma_f32_16x16x32_bf16 v[174:177], v[186:189], v[2:5], v[174:177]
	s_waitcnt vmcnt(16)
	v_mfma_f32_16x16x32_bf16 v[190:193], v[190:193], v[6:9], 0
	v_mfma_f32_16x16x32_bf16 v[190:193], v[194:197], v[10:13], v[190:193]
	v_mfma_f32_16x16x32_bf16 v[190:193], v[198:201], v[14:17], v[190:193]
	v_mfma_f32_16x16x32_bf16 v[190:193], v[202:205], v[2:5], v[190:193]
	s_waitcnt vmcnt(12)
	v_mfma_f32_16x16x32_bf16 v[206:209], v[206:209], v[6:9], 0
	v_mfma_f32_16x16x32_bf16 v[206:209], v[210:213], v[10:13], v[206:209]
	v_mfma_f32_16x16x32_bf16 v[206:209], v[214:217], v[14:17], v[206:209]
	v_mfma_f32_16x16x32_bf16 v[206:209], v[218:221], v[2:5], v[206:209]
	s_waitcnt vmcnt(8)
	v_mfma_f32_16x16x32_bf16 v[222:225], v[222:225], v[6:9], 0
	v_mfma_f32_16x16x32_bf16 v[222:225], v[226:229], v[10:13], v[222:225]
	v_mfma_f32_16x16x32_bf16 v[222:225], v[230:233], v[14:17], v[222:225]
	v_mfma_f32_16x16x32_bf16 v[222:225], v[234:237], v[2:5], v[222:225]
	s_nop 7
	s_waitcnt vmcnt(5)
	v_pk_mul_f32 v[18:19], v[18:19], v[22:23]
	v_pk_mul_f32 v[20:21], v[20:21], v[24:25]
	v_cvt_pk_bf16_f32 v18, v18, v19
	v_cvt_pk_bf16_f32 v19, v20, v21
	global_store_dwordx2 v[244:245], v[18:19], off offset:1024
	v_pk_mul_f32 v[34:35], v[34:35], v[26:27]
	v_pk_mul_f32 v[36:37], v[36:37], v[28:29]
	v_cvt_pk_bf16_f32 v34, v34, v35
	v_cvt_pk_bf16_f32 v35, v36, v37
	global_store_dwordx2 v[244:245], v[34:35], off offset:1056
	v_pk_mul_f32 v[50:51], v[50:51], v[30:31]
	v_pk_mul_f32 v[52:53], v[52:53], v[32:33]
	v_cvt_pk_bf16_f32 v50, v50, v51
	v_cvt_pk_bf16_f32 v51, v52, v53
	global_store_dwordx2 v[244:245], v[50:51], off offset:1088
	s_waitcnt vmcnt(2)
	v_pk_mul_f32 v[66:67], v[66:67], v[38:39]
	v_pk_mul_f32 v[68:69], v[68:69], v[40:41]
	v_cvt_pk_bf16_f32 v66, v66, v67
	v_cvt_pk_bf16_f32 v67, v68, v69
	global_store_dwordx2 v[244:245], v[66:67], off offset:1120
	v_pk_mul_f32 v[174:175], v[174:175], v[42:43]
	v_pk_mul_f32 v[176:177], v[176:177], v[44:45]
	v_cvt_pk_bf16_f32 v174, v174, v175
	v_cvt_pk_bf16_f32 v175, v176, v177
	global_store_dwordx2 v[244:245], v[174:175], off offset:1152
	v_pk_mul_f32 v[190:191], v[190:191], v[46:47]
	v_pk_mul_f32 v[192:193], v[192:193], v[48:49]
	v_cvt_pk_bf16_f32 v190, v190, v191
	v_cvt_pk_bf16_f32 v191, v192, v193
	global_store_dwordx2 v[244:245], v[190:191], off offset:1184
	s_waitcnt vmcnt(0)
	v_pk_mul_f32 v[206:207], v[206:207], v[54:55]
	v_pk_mul_f32 v[208:209], v[208:209], v[56:57]
	v_cvt_pk_bf16_f32 v206, v206, v207
	v_cvt_pk_bf16_f32 v207, v208, v209
	global_store_dwordx2 v[244:245], v[206:207], off offset:1216
	v_pk_mul_f32 v[222:223], v[222:223], v[58:59]
	v_pk_mul_f32 v[224:225], v[224:225], v[60:61]
	v_cvt_pk_bf16_f32 v222, v222, v223
	v_cvt_pk_bf16_f32 v223, v224, v225
	global_store_dwordx2 v[244:245], v[222:223], off offset:1248

.LBB0_817:
	s_nop 0
	global_load_ushort v2, v29, s[68:69]
	global_load_ushort v3, v29, s[66:67]
	global_load_ushort v5, v29, s[60:61]
	global_load_ushort v33, v29, s[58:59]
	global_load_ushort v34, v29, s[56:57]
	global_load_ushort v35, v29, s[50:51]
	global_load_ushort v36, v29, s[48:49]
	global_load_ushort v37, v29, s[46:47]
	global_load_ushort v38, v29, s[42:43]
	global_load_ushort v39, v29, s[40:41]
	global_load_ushort v40, v29, s[38:39]
	global_load_ushort v41, v29, s[34:35]
	global_load_ushort v42, v29, s[10:11]
	global_load_ushort v43, v29, s[30:31]
	global_load_ushort v44, v29, s[28:29]
	s_nop 0
	global_load_ushort v29, v29, s[2:3]
	s_waitcnt vmcnt(0)
	v_lshlrev_b32_e32 v1, 16, v1
	v_lshlrev_b32_e32 v10, 16, v10
	v_cndmask_b32_e64 v1, v1, v9, s[22:23]
	v_lshlrev_b32_e32 v12, 16, v12
	s_add_i32 s2, s12, s21
	v_cndmask_b32_e64 v8, v10, v8, s[22:23]
	v_add_f32_e32 v9, 0, v1
	v_cndmask_b32_e64 v12, v12, v13, s[22:23]
	s_min_u32 s0, s2, 3
	v_add_f32_e32 v9, v9, v8
	v_lshlrev_b32_e32 v6, 16, v6
	s_add_i32 s0, s0, 1
	v_add_f32_e32 v9, v9, v12
	v_cvt_f32_ubyte0_e32 v10, s0
	v_add_f32_e32 v9, v9, v6
	v_lshlrev_b32_e32 v4, 16, v4
	v_lshlrev_b32_e32 v32, 16, v32
	v_div_scale_f32 v13, s[0:1], v10, v10, v9
	v_cndmask_b32_e64 v4, v4, v30, s[22:23]
	v_cndmask_b32_e64 v30, v32, v31, s[22:23]
	v_rcp_f32_e32 v31, v13
	v_lshlrev_b32_e32 v28, 16, v28
	v_cndmask_b32_e64 v11, v28, v11, s[22:23]
	v_div_scale_f32 v28, vcc, v9, v10, v9
	v_fma_f32 v32, -v13, v31, 1.0
	v_fmac_f32_e32 v31, v32, v31
	v_mul_f32_e32 v32, v28, v31
	v_fma_f32 v45, -v13, v32, v28
	v_fmac_f32_e32 v32, v45, v31
	s_or_b32 s0, s2, 1
	v_fma_f32 v13, -v13, v32, v28
	s_min_u32 s0, s0, 3
	v_lshlrev_b32_e32 v7, 16, v7
	v_div_fmas_f32 v13, v13, v31, v32
	v_sub_f32_e32 v1, v9, v1
	s_add_i32 s0, s0, 1
	v_div_fixup_f32 v13, v13, v10, v9
	v_add_f32_e32 v1, v1, v7
	v_cvt_f32_ubyte0_e32 v9, s0
	v_sub_f32_e32 v13, v13, v6
	v_lshlrev_b32_e32 v15, 16, v15
	v_lshlrev_b32_e32 v16, 16, v16
	v_lshlrev_b32_e32 v17, 16, v17
	v_lshlrev_b32_e32 v18, 16, v18
	v_lshlrev_b32_e32 v19, 16, v19
	v_lshlrev_b32_e32 v20, 16, v20
	v_lshlrev_b32_e32 v21, 16, v21
	v_lshlrev_b32_e32 v22, 16, v22
	v_lshlrev_b32_e32 v23, 16, v23
	v_lshlrev_b32_e32 v24, 16, v24
	v_lshlrev_b32_e32 v25, 16, v25
	v_lshlrev_b32_e32 v26, 16, v26
	v_lshlrev_b32_e32 v27, 16, v27
	v_lshlrev_b32_e32 v14, 16, v14
	v_mov_b64_e32 v[78:79], v[108:109]
	v_or_b32_e32 v90, s19, v94
	v_readlane_b32 s68, v251, 60
	v_readlane_b32 s30, v251, 62
	v_readlane_b32 s34, v250, 0
	v_readlane_b32 s69, v251, 61
	v_readlane_b32 s31, v251, 63
	v_readlane_b32 s35, v250, 1
	v_lshlrev_b32_e32 v2, 16, v2
	v_lshlrev_b32_e32 v3, 16, v3
	v_lshlrev_b32_e32 v5, 16, v5
	v_lshlrev_b32_e32 v28, 16, v33
	v_lshlrev_b32_e32 v31, 16, v34
	v_lshlrev_b32_e32 v32, 16, v35
	v_lshlrev_b32_e32 v33, 16, v36
	v_lshlrev_b32_e32 v34, 16, v37
	v_lshlrev_b32_e32 v35, 16, v38
	v_lshlrev_b32_e32 v36, 16, v39
	v_lshlrev_b32_e32 v37, 16, v40
	v_lshlrev_b32_e32 v38, 16, v41
	v_lshlrev_b32_e32 v39, 16, v42
	v_div_scale_f32 v42, s[0:1], v9, v9, v1
	v_lshlrev_b32_e32 v40, 16, v43
	v_rcp_f32_e32 v43, v42
	v_lshlrev_b32_e32 v41, 16, v44
	v_bfe_u32 v44, v13, 16, 1
	v_add3_u32 v13, v13, v44, s33
	ds_write_b16_d16_hi v101, v13
	v_fma_f32 v13, -v42, v43, 1.0
	v_fmac_f32_e32 v43, v13, v43
	v_div_scale_f32 v13, vcc, v1, v9, v1
	v_mul_f32_e32 v44, v13, v43
	v_fma_f32 v45, -v42, v44, v13
	v_fmac_f32_e32 v44, v45, v43
	v_fma_f32 v13, -v42, v44, v13
	s_or_b32 s0, s2, 2
	v_div_fmas_f32 v13, v13, v43, v44
	s_min_u32 s0, s0, 3
	v_div_fixup_f32 v13, v13, v9, v1
	v_sub_f32_e32 v1, v1, v8
	s_add_i32 s0, s0, 1
	v_add_f32_e32 v1, v1, v15
	v_cvt_f32_ubyte0_e32 v8, s0
	v_div_scale_f32 v42, s[0:1], v8, v8, v1
	v_rcp_f32_e32 v43, v42
	v_sub_f32_e32 v13, v13, v7
	v_bfe_u32 v44, v13, 16, 1
	v_add3_u32 v13, v13, v44, s33
	ds_write_b16_d16_hi v101, v13 offset:272
	v_fma_f32 v13, -v42, v43, 1.0
	v_fmac_f32_e32 v43, v13, v43
	v_div_scale_f32 v13, vcc, v1, v8, v1
	v_mul_f32_e32 v44, v13, v43
	v_fma_f32 v45, -v42, v44, v13
	v_fmac_f32_e32 v44, v45, v43
	v_fma_f32 v13, -v42, v44, v13
	v_div_fmas_f32 v13, v13, v43, v44
	v_div_fixup_f32 v13, v13, v8, v1
	v_sub_f32_e32 v13, v13, v15
	v_sub_f32_e32 v1, v1, v12
	v_bfe_u32 v42, v13, 16, 1
	v_add_f32_e32 v1, v1, v16
	v_add3_u32 v13, v13, v42, s33
	v_fma_f32 v12, v1, s13, -v16
	v_sub_f32_e32 v1, v1, v6
	ds_write_b16_d16_hi v101, v13 offset:544
	v_bfe_u32 v13, v12, 16, 1
	v_add_f32_e32 v1, v1, v17
	v_add3_u32 v12, v12, v13, s33
	v_fma_f32 v6, v1, s13, -v17
	ds_write_b16_d16_hi v101, v12 offset:816
	v_bfe_u32 v12, v6, 16, 1
	v_sub_f32_e32 v1, v1, v7
	v_add3_u32 v6, v6, v12, s33
	v_add_f32_e32 v1, v1, v18
	ds_write_b16_d16_hi v101, v6 offset:1088
	v_fma_f32 v6, v1, s13, -v18
	v_bfe_u32 v7, v6, 16, 1
	v_sub_f32_e32 v1, v1, v15
	v_add3_u32 v6, v6, v7, s33
	v_add_f32_e32 v1, v1, v19
	ds_write_b16_d16_hi v101, v6 offset:1360
	v_fma_f32 v6, v1, s13, -v19
	v_bfe_u32 v7, v6, 16, 1
	v_sub_f32_e32 v1, v1, v16
	v_add3_u32 v6, v6, v7, s33
	v_add_f32_e32 v1, v1, v20
	ds_write_b16_d16_hi v101, v6 offset:1632
	v_fma_f32 v6, v1, s13, -v20
	v_bfe_u32 v7, v6, 16, 1
	v_sub_f32_e32 v1, v1, v17
	v_add3_u32 v6, v6, v7, s33
	v_add_f32_e32 v1, v1, v21
	ds_write_b16_d16_hi v101, v6 offset:1904
	v_fma_f32 v6, v1, s13, -v21
	v_bfe_u32 v7, v6, 16, 1
	v_sub_f32_e32 v1, v1, v18
	v_add3_u32 v6, v6, v7, s33
	v_add_f32_e32 v1, v1, v22
	ds_write_b16_d16_hi v101, v6 offset:2176
	v_fma_f32 v6, v1, s13, -v22
	v_bfe_u32 v7, v6, 16, 1
	v_sub_f32_e32 v1, v1, v19
	v_add3_u32 v6, v6, v7, s33
	v_add_f32_e32 v1, v1, v23
	ds_write_b16_d16_hi v101, v6 offset:2448
	v_fma_f32 v6, v1, s13, -v23
	v_bfe_u32 v7, v6, 16, 1
	v_sub_f32_e32 v1, v1, v20
	v_add3_u32 v6, v6, v7, s33
	v_add_f32_e32 v1, v1, v24
	ds_write_b16_d16_hi v101, v6 offset:2720
	v_fma_f32 v6, v1, s13, -v24
	v_bfe_u32 v7, v6, 16, 1
	v_sub_f32_e32 v1, v1, v21
	v_add3_u32 v6, v6, v7, s33
	v_add_f32_e32 v1, v1, v25
	ds_write_b16_d16_hi v101, v6 offset:2992
	v_fma_f32 v6, v1, s13, -v25
	v_bfe_u32 v7, v6, 16, 1
	v_sub_f32_e32 v1, v1, v22
	v_add3_u32 v6, v6, v7, s33
	v_add_f32_e32 v1, v1, v26
	ds_write_b16_d16_hi v101, v6 offset:3264
	v_fma_f32 v6, v1, s13, -v26
	v_bfe_u32 v7, v6, 16, 1
	v_sub_f32_e32 v1, v1, v23
	v_add3_u32 v6, v6, v7, s33
	v_add_f32_e32 v1, v1, v27
	ds_write_b16_d16_hi v101, v6 offset:3536
	v_fma_f32 v6, v1, s13, -v27
	v_bfe_u32 v7, v6, 16, 1
	v_add3_u32 v6, v6, v7, s33
	ds_write_b16_d16_hi v101, v6 offset:3808
	v_add_f32_e32 v6, 0, v11
	v_add_f32_e32 v6, v6, v30
	v_lshlrev_b32_e32 v29, 16, v29
	v_add_f32_e32 v6, v6, v4
	v_add_f32_e32 v6, v6, v29
	v_sub_f32_e32 v1, v1, v24
	v_div_scale_f32 v7, s[0:1], v10, v10, v6
	v_add_f32_e32 v1, v1, v14
	v_rcp_f32_e32 v12, v7
	v_fma_f32 v1, v1, s13, -v14
	v_bfe_u32 v13, v1, 16, 1
	v_add3_u32 v1, v1, v13, s33
	ds_write_b16_d16_hi v101, v1 offset:4080
	v_fma_f32 v1, -v7, v12, 1.0
	v_fmac_f32_e32 v12, v1, v12
	v_div_scale_f32 v1, vcc, v6, v10, v6
	v_mul_f32_e32 v13, v1, v12
	v_fma_f32 v14, -v7, v13, v1
	v_fmac_f32_e32 v13, v14, v12
	v_fma_f32 v1, -v7, v13, v1
	v_div_fmas_f32 v1, v1, v12, v13
	v_div_fixup_f32 v1, v1, v10, v6
	v_sub_f32_e32 v6, v6, v11
	v_add_f32_e32 v6, v6, v41
	v_div_scale_f32 v7, s[0:1], v9, v9, v6
	v_rcp_f32_e32 v10, v7
	v_sub_f32_e32 v1, v1, v29
	v_bfe_u32 v11, v1, 16, 1
	v_add3_u32 v1, v1, v11, s33
	ds_write_b16_d16_hi v101, v1 offset:128
	v_fma_f32 v1, -v7, v10, 1.0
	v_fmac_f32_e32 v10, v1, v10
	v_div_scale_f32 v1, vcc, v6, v9, v6
	v_mul_f32_e32 v11, v1, v10
	v_fma_f32 v12, -v7, v11, v1
	v_fmac_f32_e32 v11, v12, v10
	v_fma_f32 v1, -v7, v11, v1
	v_div_fmas_f32 v1, v1, v10, v11
	v_div_fixup_f32 v1, v1, v9, v6
	v_sub_f32_e32 v6, v6, v30
	v_add_f32_e32 v6, v6, v40
	v_div_scale_f32 v7, s[0:1], v8, v8, v6
	v_rcp_f32_e32 v9, v7
	v_sub_f32_e32 v1, v1, v41
	v_bfe_u32 v10, v1, 16, 1
	v_add3_u32 v1, v1, v10, s33
	ds_write_b16_d16_hi v101, v1 offset:400
	v_fma_f32 v1, -v7, v9, 1.0
	v_fmac_f32_e32 v9, v1, v9
	v_div_scale_f32 v1, vcc, v6, v8, v6
	v_mul_f32_e32 v10, v1, v9
	v_fma_f32 v11, -v7, v10, v1
	v_fmac_f32_e32 v10, v11, v9
	v_fma_f32 v1, -v7, v10, v1
	v_div_fmas_f32 v1, v1, v9, v10
	v_div_fixup_f32 v1, v1, v8, v6
	v_sub_f32_e32 v1, v1, v40
	v_bfe_u32 v7, v1, 16, 1
	v_add3_u32 v1, v1, v7, s33
	ds_write_b16_d16_hi v101, v1 offset:672
	v_sub_f32_e32 v1, v6, v4
	v_add_f32_e32 v1, v1, v39
	v_fma_f32 v4, v1, s13, -v39
	v_bfe_u32 v6, v4, 16, 1
	v_sub_f32_e32 v1, v1, v29
	v_add3_u32 v4, v4, v6, s33
	v_add_f32_e32 v1, v1, v38
	ds_write_b16_d16_hi v101, v4 offset:944
	v_fma_f32 v4, v1, s13, -v38
	v_bfe_u32 v6, v4, 16, 1
	v_sub_f32_e32 v1, v1, v41
	v_add3_u32 v4, v4, v6, s33
	v_add_f32_e32 v1, v1, v37
	ds_write_b16_d16_hi v101, v4 offset:1216
	v_fma_f32 v4, v1, s13, -v37
	v_bfe_u32 v6, v4, 16, 1
	v_sub_f32_e32 v1, v1, v40
	v_add3_u32 v4, v4, v6, s33
	v_add_f32_e32 v1, v1, v36
	ds_write_b16_d16_hi v101, v4 offset:1488
	v_fma_f32 v4, v1, s13, -v36
	v_bfe_u32 v6, v4, 16, 1
	v_sub_f32_e32 v1, v1, v39
	v_add3_u32 v4, v4, v6, s33
	v_add_f32_e32 v1, v1, v35
	ds_write_b16_d16_hi v101, v4 offset:1760
	v_fma_f32 v4, v1, s13, -v35
	v_bfe_u32 v6, v4, 16, 1
	v_sub_f32_e32 v1, v1, v38
	v_add3_u32 v4, v4, v6, s33
	v_add_f32_e32 v1, v1, v34
	ds_write_b16_d16_hi v101, v4 offset:2032
	v_fma_f32 v4, v1, s13, -v34
	v_bfe_u32 v6, v4, 16, 1
	v_sub_f32_e32 v1, v1, v37
	v_add3_u32 v4, v4, v6, s33
	v_add_f32_e32 v1, v1, v33
	ds_write_b16_d16_hi v101, v4 offset:2304
	v_fma_f32 v4, v1, s13, -v33
	v_bfe_u32 v6, v4, 16, 1
	v_sub_f32_e32 v1, v1, v36
	v_add3_u32 v4, v4, v6, s33
	v_add_f32_e32 v1, v1, v32
	ds_write_b16_d16_hi v101, v4 offset:2576
	v_fma_f32 v4, v1, s13, -v32
	v_bfe_u32 v6, v4, 16, 1
	v_sub_f32_e32 v1, v1, v35
	v_add3_u32 v4, v4, v6, s33
	v_add_f32_e32 v1, v1, v31
	ds_write_b16_d16_hi v101, v4 offset:2848
	v_fma_f32 v4, v1, s13, -v31
	v_bfe_u32 v6, v4, 16, 1
	v_sub_f32_e32 v1, v1, v34
	v_add3_u32 v4, v4, v6, s33
	v_add_f32_e32 v1, v1, v28
	ds_write_b16_d16_hi v101, v4 offset:3120
	v_fma_f32 v4, v1, s13, -v28
	v_bfe_u32 v6, v4, 16, 1
	v_sub_f32_e32 v1, v1, v33
	v_add3_u32 v4, v4, v6, s33
	v_add_f32_e32 v1, v1, v5
	ds_write_b16_d16_hi v101, v4 offset:3392
	v_fma_f32 v4, v1, s13, -v5
	v_sub_f32_e32 v1, v1, v32
	v_add_f32_e32 v1, v1, v3
	v_fma_f32 v3, v1, s13, -v3
	v_sub_f32_e32 v1, v1, v31
	v_bfe_u32 v5, v4, 16, 1
	v_add_f32_e32 v1, v1, v2
	v_add3_u32 v4, v4, v5, s33
	v_fma_f32 v1, v1, s13, -v2
	ds_write_b16_d16_hi v101, v4 offset:3664
	v_bfe_u32 v4, v3, 16, 1
	v_bfe_u32 v2, v1, 16, 1
	v_add3_u32 v3, v3, v4, s33
	v_add3_u32 v1, v1, v2, s33
	ds_write_b16_d16_hi v101, v3 offset:3936
	ds_write_b16_d16_hi v101, v1 offset:4208
	ds_read_b128 v[6:9], v105
	ds_read_b128 v[10:13], v105 offset:64
	ds_read_b128 v[14:17], v105 offset:128
	ds_read_b128 v[2:5], v105 offset:192
	s_mov_b64 s[38:39], 0x8080
	s_mov_b64 s[40:41], 0xc400
	s_mov_b64 s[0:1], 0
	global_load_dwordx4 v[18:21], v[78:79], off
	global_load_dwordx4 v[22:25], v[78:79], off offset:64
	global_load_dwordx4 v[26:29], v[78:79], off offset:128
	global_load_dwordx4 v[30:33], v[78:79], off offset:192
	v_add_co_u32_e32 v78, vcc, 0x1000, v78
	s_nop 1
	v_addc_co_u32_e32 v79, vcc, 0, v79, vcc
	global_load_dwordx4 v[34:37], v[78:79], off
	global_load_dwordx4 v[38:41], v[78:79], off offset:64
	global_load_dwordx4 v[42:45], v[78:79], off offset:128
	global_load_dwordx4 v[46:49], v[78:79], off offset:192
	v_add_co_u32_e32 v78, vcc, 0x1000, v78
	s_nop 1
	v_addc_co_u32_e32 v79, vcc, 0, v79, vcc
	global_load_dwordx4 v[50:53], v[78:79], off
	global_load_dwordx4 v[54:57], v[78:79], off offset:64
	global_load_dwordx4 v[58:61], v[78:79], off offset:128
	global_load_dwordx4 v[62:65], v[78:79], off offset:192
	v_add_co_u32_e32 v78, vcc, 0x1000, v78
	s_nop 1
	v_addc_co_u32_e32 v79, vcc, 0, v79, vcc
	global_load_dwordx4 v[66:69], v[78:79], off
	global_load_dwordx4 v[70:73], v[78:79], off offset:64
	global_load_dwordx4 v[74:77], v[78:79], off offset:128
	global_load_dwordx4 v[240:243], v[78:79], off offset:192
	v_add_co_u32_e32 v78, vcc, 0x1000, v78
	s_nop 1
	v_addc_co_u32_e32 v79, vcc, 0, v79, vcc
	global_load_dwordx4 v[174:177], v[78:79], off
	global_load_dwordx4 v[178:181], v[78:79], off offset:64
	global_load_dwordx4 v[182:185], v[78:79], off offset:128
	global_load_dwordx4 v[186:189], v[78:79], off offset:192
	v_add_co_u32_e32 v78, vcc, 0x1000, v78
	s_nop 1
	v_addc_co_u32_e32 v79, vcc, 0, v79, vcc
	global_load_dwordx4 v[190:193], v[78:79], off
	global_load_dwordx4 v[194:197], v[78:79], off offset:64
	global_load_dwordx4 v[198:201], v[78:79], off offset:128
	global_load_dwordx4 v[202:205], v[78:79], off offset:192
	v_add_co_u32_e32 v78, vcc, 0x1000, v78
	s_nop 1
	v_addc_co_u32_e32 v79, vcc, 0, v79, vcc
	global_load_dwordx4 v[206:209], v[78:79], off
	global_load_dwordx4 v[210:213], v[78:79], off offset:64
	global_load_dwordx4 v[214:217], v[78:79], off offset:128
	global_load_dwordx4 v[218:221], v[78:79], off offset:192
	v_add_co_u32_e32 v78, vcc, 0x1000, v78
	s_nop 1
	v_addc_co_u32_e32 v79, vcc, 0, v79, vcc
	global_load_dwordx4 v[222:225], v[78:79], off
	global_load_dwordx4 v[226:229], v[78:79], off offset:64
	global_load_dwordx4 v[230:233], v[78:79], off offset:128
	global_load_dwordx4 v[234:237], v[78:79], off offset:192
	v_lshlrev_b64 v[244:245], 11, v[90:91]
	v_lshl_add_u64 v[244:245], v[120:121], 0, v[244:245]
	s_waitcnt lgkmcnt(0)
	s_waitcnt vmcnt(28)
	v_mfma_f32_16x16x32_bf16 v[18:21], v[18:21], v[6:9], 0
	v_mfma_f32_16x16x32_bf16 v[18:21], v[22:25], v[10:13], v[18:21]
	v_mfma_f32_16x16x32_bf16 v[18:21], v[26:29], v[14:17], v[18:21]
	v_mfma_f32_16x16x32_bf16 v[18:21], v[30:33], v[2:5], v[18:21]
	s_waitcnt vmcnt(24)
	v_mfma_f32_16x16x32_bf16 v[34:37], v[34:37], v[6:9], 0
	v_mfma_f32_16x16x32_bf16 v[34:37], v[38:41], v[10:13], v[34:37]
	v_mfma_f32_16x16x32_bf16 v[34:37], v[42:45], v[14:17], v[34:37]
	v_mfma_f32_16x16x32_bf16 v[34:37], v[46:49], v[2:5], v[34:37]
	global_load_dwordx4 v[22:25], v[126:127], off offset:512
	global_load_dwordx4 v[26:29], v[126:127], off offset:576
	global_load_dwordx4 v[30:33], v[126:127], off offset:640
	s_waitcnt vmcnt(23)
	v_mfma_f32_16x16x32_bf16 v[50:53], v[50:53], v[6:9], 0
	v_mfma_f32_16x16x32_bf16 v[50:53], v[54:57], v[10:13], v[50:53]
	v_mfma_f32_16x16x32_bf16 v[50:53], v[58:61], v[14:17], v[50:53]
	v_mfma_f32_16x16x32_bf16 v[50:53], v[62:65], v[2:5], v[50:53]
	global_load_dwordx4 v[38:41], v[126:127], off offset:704
	global_load_dwordx4 v[42:45], v[126:127], off offset:768
	global_load_dwordx4 v[46:49], v[126:127], off offset:832
	s_waitcnt vmcnt(22)
	v_mfma_f32_16x16x32_bf16 v[66:69], v[66:69], v[6:9], 0
	v_mfma_f32_16x16x32_bf16 v[66:69], v[70:73], v[10:13], v[66:69]
	v_mfma_f32_16x16x32_bf16 v[66:69], v[74:77], v[14:17], v[66:69]
	v_mfma_f32_16x16x32_bf16 v[66:69], v[240:243], v[2:5], v[66:69]
	global_load_dwordx4 v[54:57], v[126:127], off offset:896
	global_load_dwordx4 v[58:61], v[126:127], off offset:960
	s_waitcnt vmcnt(20)
	v_mfma_f32_16x16x32_bf16 v[174:177], v[174:177], v[6:9], 0
	v_mfma_f32_16x16x32_bf16 v[174:177], v[178:181], v[10:13], v[174:177]
	v_mfma_f32_16x16x32_bf16 v[174:177], v[182:185], v[14:17], v[174:177]
	v_mfma_f32_16x16x32_bf16 v[174:177], v[186:189], v[2:5], v[174:177]
	s_waitcnt vmcnt(16)
	v_mfma_f32_16x16x32_bf16 v[190:193], v[190:193], v[6:9], 0
	v_mfma_f32_16x16x32_bf16 v[190:193], v[194:197], v[10:13], v[190:193]
	v_mfma_f32_16x16x32_bf16 v[190:193], v[198:201], v[14:17], v[190:193]
	v_mfma_f32_16x16x32_bf16 v[190:193], v[202:205], v[2:5], v[190:193]
	s_waitcnt vmcnt(12)
	v_mfma_f32_16x16x32_bf16 v[206:209], v[206:209], v[6:9], 0
	v_mfma_f32_16x16x32_bf16 v[206:209], v[210:213], v[10:13], v[206:209]
	v_mfma_f32_16x16x32_bf16 v[206:209], v[214:217], v[14:17], v[206:209]
	v_mfma_f32_16x16x32_bf16 v[206:209], v[218:221], v[2:5], v[206:209]
	s_waitcnt vmcnt(8)
	v_mfma_f32_16x16x32_bf16 v[222:225], v[222:225], v[6:9], 0
	v_mfma_f32_16x16x32_bf16 v[222:225], v[226:229], v[10:13], v[222:225]
	v_mfma_f32_16x16x32_bf16 v[222:225], v[230:233], v[14:17], v[222:225]
	v_mfma_f32_16x16x32_bf16 v[222:225], v[234:237], v[2:5], v[222:225]
	s_nop 7
	s_waitcnt vmcnt(5)
	v_pk_mul_f32 v[18:19], v[18:19], v[22:23]
	v_pk_mul_f32 v[20:21], v[20:21], v[24:25]
	v_cvt_pk_bf16_f32 v18, v18, v19
	v_cvt_pk_bf16_f32 v19, v20, v21
	global_store_dwordx2 v[244:245], v[18:19], off offset:1280
	v_pk_mul_f32 v[34:35], v[34:35], v[26:27]
	v_pk_mul_f32 v[36:37], v[36:37], v[28:29]
	v_cvt_pk_bf16_f32 v34, v34, v35
	v_cvt_pk_bf16_f32 v35, v36, v37
	global_store_dwordx2 v[244:245], v[34:35], off offset:1312
	v_pk_mul_f32 v[50:51], v[50:51], v[30:31]
	v_pk_mul_f32 v[52:53], v[52:53], v[32:33]
	v_cvt_pk_bf16_f32 v50, v50, v51
	v_cvt_pk_bf16_f32 v51, v52, v53
	global_store_dwordx2 v[244:245], v[50:51], off offset:1344
	s_waitcnt vmcnt(2)
	v_pk_mul_f32 v[66:67], v[66:67], v[38:39]
	v_pk_mul_f32 v[68:69], v[68:69], v[40:41]
	v_cvt_pk_bf16_f32 v66, v66, v67
	v_cvt_pk_bf16_f32 v67, v68, v69
	global_store_dwordx2 v[244:245], v[66:67], off offset:1376
	v_pk_mul_f32 v[174:175], v[174:175], v[42:43]
	v_pk_mul_f32 v[176:177], v[176:177], v[44:45]
	v_cvt_pk_bf16_f32 v174, v174, v175
	v_cvt_pk_bf16_f32 v175, v176, v177
	global_store_dwordx2 v[244:245], v[174:175], off offset:1408
	v_pk_mul_f32 v[190:191], v[190:191], v[46:47]
	v_pk_mul_f32 v[192:193], v[192:193], v[48:49]
	v_cvt_pk_bf16_f32 v190, v190, v191
	v_cvt_pk_bf16_f32 v191, v192, v193
	global_store_dwordx2 v[244:245], v[190:191], off offset:1440
	s_waitcnt vmcnt(0)
	v_pk_mul_f32 v[206:207], v[206:207], v[54:55]
	v_pk_mul_f32 v[208:209], v[208:209], v[56:57]
	v_cvt_pk_bf16_f32 v206, v206, v207
	v_cvt_pk_bf16_f32 v207, v208, v209
	global_store_dwordx2 v[244:245], v[206:207], off offset:1472
	v_pk_mul_f32 v[222:223], v[222:223], v[58:59]
	v_pk_mul_f32 v[224:225], v[224:225], v[60:61]
	v_cvt_pk_bf16_f32 v222, v222, v223
	v_cvt_pk_bf16_f32 v223, v224, v225
	global_store_dwordx2 v[244:245], v[222:223], off offset:1504
	s_branch .LBB0_819
